# accumulator zeroing with 64-bit moves; out-projection epilogue fetches both halves' residual rows up front (one exposed round trip per tile)
# speedup vs baseline: 1.0018x; 1.0018x over previous
;     __device__ bool next(int i, pg8::Unit& u) const { const int cnt = (nwg - c + G - 1) / G; if (i >= reps * cnt) return false; return pg8::StaticOrder::next(i % cnt, u); }
; template <class Epi, class Sched, bool ALIGN_EPI = false, bool SP2 = false>
; __device__ __forceinline__ void gemm_phase(PG8_LAS unsigned char* lds, const Gemm g, const Sched& S, const Epi& E) {
;     ...
;         const bool has_next = S.next(ui + 1, nxt);
;         const char* nA = has_next ? (const char*)g.A + (size_t)nxt.pm * tstep : cA; const char* nB = has_next ? (const char*)g.Bt + (size_t)nxt.pn * tstep : cB;
;         for (int t = 0; t < nt; t += 2) {
;             const bool last = (t == nt - 2);
;             const char* a1 = cA + (size_t)(t + 1) * kstep;
;             const char* a2 = last ? nA : cA + (size_t)(t + 2) * kstep; const char* b2 = last ? nB : cB + (size_t)(t + 2) * kstep;
;     ...
; #pragma unroll
;         for (int a = 0; a < 2; ++a)
; #pragma unroll
;             for (int b = 0; b < 2; ++b)
; #pragma unroll
;                 for (int m = 0; m < 4; ++m)
; #pragma unroll
;                     for (int n = 0; n < 2; ++n) acc[a][b][m][n] = (f32x4){0.f, 0.f, 0.f, 0.f};
.LBB0_128:
	s_ashr_i32 s25, s24, 31
	s_lshl_b64 s[28:29], s[24:25], 20
	v_readlane_b32 s30, v254, 51
	v_readlane_b32 s31, v254, 52
	s_add_u32 s28, s30, s28
	s_addc_u32 s29, s31, s29
	s_and_b64 s[30:31], s[26:27], exec
	s_cselect_b32 s25, s29, s9
	s_cselect_b32 s35, s28, s8
	s_ashr_i32 s23, s22, 31
	s_lshl_b64 s[30:31], s[22:23], 20
	s_add_u32 s30, s94, s30
	s_addc_u32 s31, s95, s31
	s_and_b64 s[46:47], s[26:27], exec
	s_cselect_b32 s23, s31, s45
	s_cselect_b32 s43, s30, s44
	s_add_u32 s8, s8, 0x80080
	s_addc_u32 s9, s9, 0
	s_add_u32 s48, s44, 0x100
	v_mov_b64_e32 v[0:1], 0
	v_mov_b64_e32 v[2:3], 0
	v_mov_b64_e32 v[4:5], 0
	v_mov_b64_e32 v[6:7], 0
	v_mov_b64_e32 v[8:9], 0
	v_mov_b64_e32 v[10:11], 0
	v_mov_b64_e32 v[12:13], 0
	v_mov_b64_e32 v[14:15], 0
	v_mov_b64_e32 v[16:17], 0
	v_mov_b64_e32 v[18:19], 0
	v_mov_b64_e32 v[20:21], 0
	v_mov_b64_e32 v[22:23], 0
	v_mov_b64_e32 v[24:25], 0
	v_mov_b64_e32 v[26:27], 0
	v_mov_b64_e32 v[28:29], 0
	v_mov_b64_e32 v[30:31], 0
	v_mov_b64_e32 v[32:33], 0
	v_mov_b64_e32 v[34:35], 0
	v_mov_b64_e32 v[36:37], 0
	v_mov_b64_e32 v[38:39], 0
	v_mov_b64_e32 v[40:41], 0
	v_mov_b64_e32 v[42:43], 0
	v_mov_b64_e32 v[44:45], 0
	v_mov_b64_e32 v[46:47], 0
	v_mov_b64_e32 v[48:49], 0
	v_mov_b64_e32 v[50:51], 0
	v_mov_b64_e32 v[52:53], 0
	v_mov_b64_e32 v[54:55], 0
	v_mov_b64_e32 v[56:57], 0
	v_mov_b64_e32 v[58:59], 0
	v_mov_b64_e32 v[60:61], 0
	v_mov_b64_e32 v[62:63], 0
	v_mov_b64_e32 v[64:65], 0
	v_mov_b64_e32 v[66:67], 0
	v_mov_b64_e32 v[68:69], 0
	v_mov_b64_e32 v[70:71], 0
	v_mov_b64_e32 v[72:73], 0
	v_mov_b64_e32 v[74:75], 0
	v_mov_b64_e32 v[76:77], 0
	v_mov_b64_e32 v[78:79], 0
	v_mov_b64_e32 v[80:81], 0
	v_mov_b64_e32 v[82:83], 0
	v_mov_b64_e32 v[84:85], 0
	v_mov_b64_e32 v[86:87], 0
	v_mov_b64_e32 v[88:89], 0
	v_mov_b64_e32 v[90:91], 0
	v_mov_b64_e32 v[92:93], 0
	v_mov_b64_e32 v[94:95], 0
	v_mov_b64_e32 v[108:109], 0
	v_mov_b64_e32 v[110:111], 0
	v_mov_b64_e32 v[116:117], 0
	v_mov_b64_e32 v[118:119], 0
	v_mov_b64_e32 v[120:121], 0
	v_mov_b64_e32 v[122:123], 0
	v_mov_b64_e32 v[124:125], 0
	v_mov_b64_e32 v[126:127], 0
	v_mov_b64_e32 v[128:129], 0
	v_mov_b64_e32 v[130:131], 0
	v_mov_b64_e32 v[132:133], 0
	v_mov_b64_e32 v[134:135], 0
	v_mov_b64_e32 v[136:137], 0
	v_mov_b64_e32 v[138:139], 0
	v_mov_b64_e32 v[140:141], 0
	v_mov_b64_e32 v[142:143], 0
	s_addc_u32 s49, s45, 0
	s_mov_b32 s54, -2
	s_waitcnt lgkmcnt(0)

;     __device__ bool next(int i, pg8::Unit& u) const { const int cnt = (nwg - c + G - 1) / G; if (i >= reps * cnt) return false; return pg8::StaticOrder::next(i % cnt, u); }
; template <class Epi, class Sched, bool ALIGN_EPI = false, bool SP2 = false>
; __device__ __forceinline__ void gemm_phase(PG8_LAS unsigned char* lds, const Gemm g, const Sched& S, const Epi& E) {
;     ...
;         const bool has_next = S.next(ui + 1, nxt);
;         const char* nA = has_next ? (const char*)g.A + (size_t)nxt.pm * tstep : cA; const char* nB = has_next ? (const char*)g.Bt + (size_t)nxt.pn * tstep : cB;
;         for (int t = 0; t < nt; t += 2) {
;             const bool last = (t == nt - 2);
;             const char* a1 = cA + (size_t)(t + 1) * kstep;
;             const char* a2 = last ? nA : cA + (size_t)(t + 2) * kstep; const char* b2 = last ? nB : cB + (size_t)(t + 2) * kstep;
;     ...
; #pragma unroll
;         for (int a = 0; a < 2; ++a)
; #pragma unroll
;             for (int b = 0; b < 2; ++b)
; #pragma unroll
;                 for (int m = 0; m < 4; ++m)
; #pragma unroll
;                     for (int n = 0; n < 2; ++n) acc[a][b][m][n] = (f32x4){0.f, 0.f, 0.f, 0.f};
.LBB0_306:
	s_ashr_i32 s21, s20, 31
	s_lshl_b64 s[22:23], s[20:21], 20
	s_add_u32 s22, s60, s22
	s_addc_u32 s23, s61, s23
	s_and_b64 s[24:25], s[4:5], exec
	s_cselect_b32 s7, s23, s27
	s_cselect_b32 s21, s22, s26
	s_ashr_i32 s19, s18, 31
	s_lshl_b64 s[24:25], s[18:19], 20
	s_add_u32 s24, s68, s24
	s_addc_u32 s25, s69, s25
	s_and_b64 s[30:31], s[4:5], exec
	s_cselect_b32 s19, s25, s29
	s_cselect_b32 s33, s24, s28
	s_add_u32 s26, s26, 0x80080
	s_addc_u32 s27, s27, 0
	s_add_u32 s48, s28, 0x100
	v_mov_b64_e32 v[0:1], 0
	v_mov_b64_e32 v[2:3], 0
	v_mov_b64_e32 v[4:5], 0
	v_mov_b64_e32 v[6:7], 0
	v_mov_b64_e32 v[8:9], 0
	v_mov_b64_e32 v[10:11], 0
	v_mov_b64_e32 v[12:13], 0
	v_mov_b64_e32 v[14:15], 0
	v_mov_b64_e32 v[16:17], 0
	v_mov_b64_e32 v[18:19], 0
	v_mov_b64_e32 v[20:21], 0
	v_mov_b64_e32 v[22:23], 0
	v_mov_b64_e32 v[24:25], 0
	v_mov_b64_e32 v[26:27], 0
	v_mov_b64_e32 v[28:29], 0
	v_mov_b64_e32 v[30:31], 0
	v_mov_b64_e32 v[32:33], 0
	v_mov_b64_e32 v[34:35], 0
	v_mov_b64_e32 v[36:37], 0
	v_mov_b64_e32 v[38:39], 0
	v_mov_b64_e32 v[40:41], 0
	v_mov_b64_e32 v[42:43], 0
	v_mov_b64_e32 v[44:45], 0
	v_mov_b64_e32 v[46:47], 0
	v_mov_b64_e32 v[48:49], 0
	v_mov_b64_e32 v[50:51], 0
	v_mov_b64_e32 v[52:53], 0
	v_mov_b64_e32 v[54:55], 0
	v_mov_b64_e32 v[56:57], 0
	v_mov_b64_e32 v[58:59], 0
	v_mov_b64_e32 v[60:61], 0
	v_mov_b64_e32 v[62:63], 0
	v_mov_b64_e32 v[64:65], 0
	v_mov_b64_e32 v[66:67], 0
	v_mov_b64_e32 v[68:69], 0
	v_mov_b64_e32 v[70:71], 0
	v_mov_b64_e32 v[72:73], 0
	v_mov_b64_e32 v[74:75], 0
	v_mov_b64_e32 v[76:77], 0
	v_mov_b64_e32 v[78:79], 0
	v_mov_b64_e32 v[80:81], 0
	v_mov_b64_e32 v[82:83], 0
	v_mov_b64_e32 v[84:85], 0
	v_mov_b64_e32 v[86:87], 0
	v_mov_b64_e32 v[88:89], 0
	v_mov_b64_e32 v[90:91], 0
	v_mov_b64_e32 v[92:93], 0
	v_mov_b64_e32 v[94:95], 0
	v_mov_b64_e32 v[96:97], 0
	v_mov_b64_e32 v[98:99], 0
	v_mov_b64_e32 v[100:101], 0
	v_mov_b64_e32 v[102:103], 0
	v_mov_b64_e32 v[104:105], 0
	v_mov_b64_e32 v[106:107], 0
	v_mov_b64_e32 v[108:109], 0
	v_mov_b64_e32 v[110:111], 0
	v_mov_b64_e32 v[112:113], 0
	v_mov_b64_e32 v[114:115], 0
	v_mov_b64_e32 v[116:117], 0
	v_mov_b64_e32 v[118:119], 0
	v_mov_b64_e32 v[120:121], 0
	v_mov_b64_e32 v[122:123], 0
	v_mov_b64_e32 v[124:125], 0
	v_mov_b64_e32 v[126:127], 0
	s_addc_u32 s49, s29, 0
	s_mov_b32 s50, -2
	s_waitcnt lgkmcnt(0)
	s_waitcnt lgkmcnt(0)

; __device__ __forceinline__ unsigned cvt_pk_bf16(float lo, float hi) { f32x2 v = {lo, hi}; return __builtin_bit_cast(unsigned, __builtin_convertvector(v, bf2_t)); }
;     __device__ __forceinline__ void operator()(const f32x4 (&acc)[2][2][4][2], const Unit& u, int wr, int wc, int fr, int fq) const {
;         const int row0 = u.pm * BM + wr * 64 + fr, col0 = u.pn * BM + wc * 32 + 8 * fq;
; #pragma unroll
;         for (int ai = 0; ai < 2; ++ai) {
;             u32x4 raw[4][2];
; #pragma unroll
;             for (int m = 0; m < 4; ++m)
; #pragma unroll
;                 for (int bj = 0; bj < 2; ++bj) raw[m][bj] = *(const u32x4*)(base16 + (size_t)(row0 + ai * HALF + m * 16) * 2048 + col0 + bj * HALF);
; #pragma unroll
;             for (int m = 0; m < 4; ++m) {
;                 const int row = row0 + ai * HALF + m * 16;
;                 const size_t off = (size_t)row * 2048 + col0;
;                 float sq = 0.f;
; #pragma unroll
;                 for (int bj = 0; bj < 2; ++bj) {
;                     const u32x4 w = raw[m][bj];
;                     const f32x4 r0 = {__uint_as_float(w.x << 16), __uint_as_float(w.x & 0xffff0000u), __uint_as_float(w.y << 16), __uint_as_float(w.y & 0xffff0000u)};
;                     const f32x4 r1 = {__uint_as_float(w.z << 16), __uint_as_float(w.z & 0xffff0000u), __uint_as_float(w.w << 16), __uint_as_float(w.w & 0xffff0000u)};
;                     const f32x4 v0 = r0 + acc[ai][bj][m][0], v1 = r1 + acc[ai][bj][m][1];
;                     if (out32) { *(f32x4*)(out32 + off + bj * HALF) = v0; *(f32x4*)(out32 + off + bj * HALF + 4) = v1; }
;                     if (XB) { u32x4 o; o.x = cvt_pk_bf16(v0[0], v0[1]); o.y = cvt_pk_bf16(v0[2], v0[3]); o.z = cvt_pk_bf16(v1[0], v1[1]); o.w = cvt_pk_bf16(v1[2], v1[3]);
;                               *(u32x4*)(XB + off + bj * HALF) = o;
;                               sq += ((v0[0] * v0[0] + v0[1] * v0[1]) + (v0[2] * v0[2] + v0[3] * v0[3])) + ((v1[0] * v1[0] + v1[1] * v1[1]) + (v1[2] * v1[2] + v1[3] * v1[3])); }
;                 }
;                 if (XB) { sq += __shfl_xor(sq, 16); sq += __shfl_xor(sq, 32); if (fq == 0) SS[(size_t)row * 32 + u.pn * 4 + wc] = sq; }
;             }
.LBB0_310:
	v_lshl_or_b32 v128, s6, 8, v180
	v_lshl_add_u32 v170, s8, 8, v178
	v_ashrrev_i32_e32 v129, 31, v128
	s_lshl_b32 s26, s6, 2
	v_readlane_b32 s6, v254, 51
	v_lshlrev_b64 v[194:195], 1, v[128:129]
	v_readlane_b32 s7, v254, 52
	v_ashrrev_i32_e32 v171, 31, v170
	v_lshlrev_b64 v[198:199], 12, v[170:171]
	v_lshl_add_u64 v[168:169], s[6:7], 0, v[194:195]
	v_or_b32_e32 v176, 16, v170
	v_lshl_add_u64 v[128:129], v[168:169], 0, v[198:199]
	v_ashrrev_i32_e32 v177, 31, v176
	global_load_dwordx4 v[186:189], v[128:129], off
	global_load_dwordx4 v[190:193], v[128:129], off offset:256
	v_lshlrev_b64 v[128:129], 12, v[176:177]
	v_or_b32_e32 v174, 32, v170
	v_lshl_add_u64 v[128:129], v[168:169], 0, v[128:129]
	v_ashrrev_i32_e32 v175, 31, v174
	global_load_dwordx4 v[148:151], v[128:129], off
	global_load_dwordx4 v[144:147], v[128:129], off offset:256
	v_lshlrev_b64 v[128:129], 12, v[174:175]
	v_or_b32_e32 v172, 48, v170
	v_lshl_add_u64 v[128:129], v[168:169], 0, v[128:129]
	v_ashrrev_i32_e32 v173, 31, v172
	global_load_dwordx4 v[140:143], v[128:129], off
	global_load_dwordx4 v[136:139], v[128:129], off offset:256
	v_lshlrev_b64 v[128:129], 12, v[172:173]
	v_lshl_add_u64 v[128:129], v[168:169], 0, v[128:129]
	global_load_dwordx4 v[132:135], v[128:129], off
	s_nop 0
	global_load_dwordx4 v[128:131], v[128:129], off offset:256
	v_lshl_add_u64 v[198:199], s[6:7], 0, v[198:199]
	v_lshl_add_u64 v[194:195], v[198:199], 0, v[194:195]
	v_cndmask_b32_e64 v185, 0, 1, s[16:17]
	s_ashr_i32 s27, s26, 31
	v_cmp_ne_u32_e64 s[6:7], 1, v185
	s_andn2_b64 vcc, exec, s[16:17]
	v_add_u32_e32 v244, 0x80, v170
	v_ashrrev_i32_e32 v245, 31, v244
	v_lshlrev_b64 v[244:245], 12, v[244:245]
	v_lshl_add_u64 v[244:245], v[168:169], 0, v[244:245]
	global_load_dwordx4 v[206:209], v[244:245], off
	global_load_dwordx4 v[210:213], v[244:245], off offset:256
	v_add_u32_e32 v244, 0x90, v170
	v_ashrrev_i32_e32 v245, 31, v244
	v_lshlrev_b64 v[244:245], 12, v[244:245]
	v_lshl_add_u64 v[244:245], v[168:169], 0, v[244:245]
	global_load_dwordx4 v[214:217], v[244:245], off
	global_load_dwordx4 v[218:221], v[244:245], off offset:256
	v_add_u32_e32 v244, 0xa0, v170
	v_ashrrev_i32_e32 v245, 31, v244
	v_lshlrev_b64 v[244:245], 12, v[244:245]
	v_lshl_add_u64 v[244:245], v[168:169], 0, v[244:245]
	global_load_dwordx4 v[228:231], v[244:245], off
	global_load_dwordx4 v[232:235], v[244:245], off offset:256
	v_add_u32_e32 v244, 0xb0, v170
	v_ashrrev_i32_e32 v245, 31, v244
	v_lshlrev_b64 v[244:245], 12, v[244:245]
	v_lshl_add_u64 v[244:245], v[168:169], 0, v[244:245]
	global_load_dwordx4 v[236:239], v[244:245], off
	global_load_dwordx4 v[240:243], v[244:245], off offset:256
	s_waitcnt vmcnt(0)
	v_lshlrev_b32_e32 v200, 16, v186
	v_and_b32_e32 v201, 0xffff0000, v186
	v_lshlrev_b32_e32 v186, 16, v187
	v_and_b32_e32 v187, 0xffff0000, v187
	v_lshlrev_b32_e32 v202, 16, v188
	v_and_b32_e32 v203, 0xffff0000, v188
	v_lshlrev_b32_e32 v188, 16, v189
	v_and_b32_e32 v189, 0xffff0000, v189
	v_pk_add_f32 v[126:127], v[126:127], v[186:187]
	v_pk_add_f32 v[124:125], v[124:125], v[200:201]
	v_pk_add_f32 v[122:123], v[122:123], v[188:189]
	v_pk_add_f32 v[120:121], v[120:121], v[202:203]
	v_cvt_pk_bf16_f32 v186, v124, v125
	v_cvt_pk_bf16_f32 v187, v126, v127
	v_cvt_pk_bf16_f32 v188, v120, v121
	v_cvt_pk_bf16_f32 v189, v122, v123
	global_store_dwordx4 v[194:195], v[186:189], off
	s_nop 1
	v_lshlrev_b32_e32 v186, 16, v190
	v_and_b32_e32 v187, 0xffff0000, v190
	v_lshlrev_b32_e32 v188, 16, v191
	v_and_b32_e32 v189, 0xffff0000, v191
	v_lshlrev_b32_e32 v190, 16, v192
	v_and_b32_e32 v191, 0xffff0000, v192
	v_lshlrev_b32_e32 v192, 16, v193
	v_and_b32_e32 v193, 0xffff0000, v193
	v_pk_add_f32 v[118:119], v[118:119], v[188:189]
	v_pk_add_f32 v[116:117], v[116:117], v[186:187]
	v_pk_add_f32 v[114:115], v[114:115], v[192:193]
	v_pk_add_f32 v[112:113], v[112:113], v[190:191]
	v_cvt_pk_bf16_f32 v186, v116, v117
	v_cvt_pk_bf16_f32 v187, v118, v119
	v_cvt_pk_bf16_f32 v188, v112, v113
	v_cvt_pk_bf16_f32 v189, v114, v115
	global_store_dwordx4 v[194:195], v[186:189], off offset:256
	s_cbranch_vccnz .LBB0_314
	v_mul_f32_e32 v113, v113, v113
	v_mul_f32_e32 v125, v125, v125
	v_mul_f32_e32 v121, v121, v121
	v_mul_f32_e32 v117, v117, v117
	v_fmac_f32_e32 v113, v112, v112
	v_mul_f32_e32 v112, v115, v115
	v_fmac_f32_e32 v125, v124, v124
	v_mul_f32_e32 v124, v127, v127
	v_fmac_f32_e32 v121, v120, v120
	v_mul_f32_e32 v120, v123, v123
	v_fmac_f32_e32 v117, v116, v116
	v_mul_f32_e32 v116, v119, v119
	v_fmac_f32_e32 v112, v114, v114
	v_and_b32_e32 v114, 64, v184
	v_fmac_f32_e32 v124, v126, v126
	v_fmac_f32_e32 v120, v122, v122
	v_fmac_f32_e32 v116, v118, v118
	v_add_f32_e32 v112, v113, v112
	v_xor_b32_e32 v113, 16, v184
	v_add_u32_e32 v114, 64, v114
	v_add_f32_e32 v124, v125, v124
	v_add_f32_e32 v120, v121, v120
	v_add_f32_e32 v116, v117, v116
	v_cmp_lt_i32_e32 vcc, v113, v114
	v_add_f32_e32 v120, v124, v120
	v_add_f32_e32 v112, v116, v112
	v_cndmask_b32_e32 v113, v184, v113, vcc
	v_add_f32_e32 v112, v120, v112
	v_lshlrev_b32_e32 v113, 2, v113
	ds_bpermute_b32 v113, v113, v112
	s_waitcnt lgkmcnt(0)
	v_add_f32_e32 v112, v112, v113
	v_xor_b32_e32 v113, 32, v184
	v_cmp_lt_i32_e32 vcc, v113, v114
	s_nop 1
	v_cndmask_b32_e32 v113, v184, v113, vcc
	v_lshlrev_b32_e32 v113, 2, v113
	ds_bpermute_b32 v113, v113, v112
	s_and_saveexec_b64 s[28:29], s[2:3]
	s_cbranch_execz .LBB0_313
	v_readlane_b32 s30, v254, 57
	v_lshlrev_b64 v[114:115], 7, v[170:171]
	v_readlane_b32 s31, v254, 58
	s_lshl_b32 s8, s43, 2
	s_waitcnt lgkmcnt(0)
	v_add_f32_e32 v112, v112, v113
	v_lshl_add_u64 v[114:115], s[30:31], 0, v[114:115]
	v_lshl_add_u64 v[114:115], s[26:27], 2, v[114:115]
	v_lshl_add_u64 v[114:115], v[114:115], 0, s[8:9]
	global_store_dword v[114:115], v112, off

; __device__ __forceinline__ unsigned cvt_pk_bf16(float lo, float hi) { f32x2 v = {lo, hi}; return __builtin_bit_cast(unsigned, __builtin_convertvector(v, bf2_t)); }
;     __device__ __forceinline__ void operator()(const f32x4 (&acc)[2][2][4][2], const Unit& u, int wr, int wc, int fr, int fq) const {
;     ...
;         for (int ai = 0; ai < 2; ++ai) {
;             u32x4 raw[4][2];
; #pragma unroll
;             for (int m = 0; m < 4; ++m)
; #pragma unroll
;                 for (int bj = 0; bj < 2; ++bj) raw[m][bj] = *(const u32x4*)(base16 + (size_t)(row0 + ai * HALF + m * 16) * 2048 + col0 + bj * HALF);
; #pragma unroll
;             for (int m = 0; m < 4; ++m) {
;                 const int row = row0 + ai * HALF + m * 16;
;                 const size_t off = (size_t)row * 2048 + col0;
;                 float sq = 0.f;
; #pragma unroll
;                 for (int bj = 0; bj < 2; ++bj) {
;                     const u32x4 w = raw[m][bj];
;                     const f32x4 r0 = {__uint_as_float(w.x << 16), __uint_as_float(w.x & 0xffff0000u), __uint_as_float(w.y << 16), __uint_as_float(w.y & 0xffff0000u)};
;                     const f32x4 r1 = {__uint_as_float(w.z << 16), __uint_as_float(w.z & 0xffff0000u), __uint_as_float(w.w << 16), __uint_as_float(w.w & 0xffff0000u)};
;                     const f32x4 v0 = r0 + acc[ai][bj][m][0], v1 = r1 + acc[ai][bj][m][1];
;                     if (out32) { *(f32x4*)(out32 + off + bj * HALF) = v0; *(f32x4*)(out32 + off + bj * HALF + 4) = v1; }
;                     if (XB) { u32x4 o; o.x = cvt_pk_bf16(v0[0], v0[1]); o.y = cvt_pk_bf16(v0[2], v0[3]); o.z = cvt_pk_bf16(v1[0], v1[1]); o.w = cvt_pk_bf16(v1[2], v1[3]);
;                               *(u32x4*)(XB + off + bj * HALF) = o;
;                               sq += ((v0[0] * v0[0] + v0[1] * v0[1]) + (v0[2] * v0[2] + v0[3] * v0[3])) + ((v1[0] * v1[0] + v1[1] * v1[1]) + (v1[2] * v1[2] + v1[3] * v1[3])); }
;                 }
;                 if (XB) { sq += __shfl_xor(sq, 16); sq += __shfl_xor(sq, 32); if (fq == 0) SS[(size_t)row * 32 + u.pn * 4 + wc] = sq; }
;             }
.LBB0_335:
	v_add_u32_e32 v98, 0x80, v170
	v_ashrrev_i32_e32 v99, 31, v98
	v_add_u32_e32 v96, 0x90, v170
	s_waitcnt lgkmcnt(0)
	v_lshlrev_b64 v[64:65], 12, v[98:99]
	v_ashrrev_i32_e32 v97, 31, v96
	v_add_u32_e32 v94, 0xa0, v170
	v_lshl_add_u64 v[102:103], v[168:169], 0, v[64:65]
	v_lshlrev_b64 v[64:65], 12, v[96:97]
	v_ashrrev_i32_e32 v95, 31, v94
	v_add_u32_e32 v92, 0xb0, v170
	v_lshl_add_u64 v[64:65], v[168:169], 0, v[64:65]
	v_lshlrev_b64 v[66:67], 12, v[94:95]
	v_ashrrev_i32_e32 v93, 31, v92
	v_mov_b64_e32 v[88:89], v[210:211]
	v_mov_b64_e32 v[90:91], v[212:213]
	v_mov_b64_e32 v[84:85], v[214:215]
	v_mov_b64_e32 v[86:87], v[216:217]
	v_lshl_add_u64 v[66:67], v[168:169], 0, v[66:67]
	v_mov_b64_e32 v[80:81], v[218:219]
	v_mov_b64_e32 v[82:83], v[220:221]
	v_mov_b64_e32 v[76:77], v[228:229]
	v_mov_b64_e32 v[78:79], v[230:231]
	v_lshlrev_b64 v[64:65], 12, v[92:93]
	v_lshl_add_u64 v[64:65], v[168:169], 0, v[64:65]
	v_mov_b64_e32 v[72:73], v[232:233]
	v_mov_b64_e32 v[74:75], v[234:235]
	v_mov_b64_e32 v[68:69], v[236:237]
	v_mov_b64_e32 v[70:71], v[238:239]
	v_mov_b64_e32 v[64:65], v[240:241]
	v_mov_b64_e32 v[66:67], v[242:243]
	v_lshlrev_b64 v[100:101], 11, v[98:99]
	s_and_b64 vcc, exec, s[6:7]
	v_lshl_add_u64 v[100:101], v[100:101], 1, v[168:169]
	s_cbranch_vccnz .LBB0_337
	v_mov_b64_e32 v[102:103], v[206:207]
	v_mov_b64_e32 v[104:105], v[208:209]
	v_lshlrev_b32_e32 v106, 16, v104
	v_and_b32_e32 v107, 0xffff0000, v104
	v_lshlrev_b32_e32 v104, 16, v105
	v_and_b32_e32 v105, 0xffff0000, v105
	v_pk_add_f32 v[62:63], v[62:63], v[104:105]
	v_lshlrev_b32_e32 v104, 16, v102
	v_and_b32_e32 v105, 0xffff0000, v102
	v_lshlrev_b32_e32 v102, 16, v103
	v_and_b32_e32 v103, 0xffff0000, v103
	v_pk_add_f32 v[60:61], v[60:61], v[106:107]
	v_pk_add_f32 v[102:103], v[58:59], v[102:103]
	v_pk_add_f32 v[104:105], v[56:57], v[104:105]
	v_cvt_pk_bf16_f32 v57, v102, v103
	v_cvt_pk_bf16_f32 v56, v104, v105
	v_cvt_pk_bf16_f32 v58, v60, v61
	v_cvt_pk_bf16_f32 v59, v62, v63
	global_store_dwordx4 v[100:101], v[56:59], off
	s_nop 1
	v_mov_b32_e32 v57, v60
	v_mov_b32_e32 v60, v105
	v_mov_b32_e32 v56, v104
	v_pk_mul_f32 v[58:59], v[60:61], v[60:61]
	s_nop 0
	v_pk_fma_f32 v[56:57], v[56:57], v[56:57], v[58:59]
	v_mov_b32_e32 v59, v62
	v_mov_b32_e32 v62, v103
	v_mov_b32_e32 v58, v102
	v_pk_mul_f32 v[60:61], v[62:63], v[62:63]
	s_nop 0
	v_pk_fma_f32 v[58:59], v[58:59], v[58:59], v[60:61]
	s_nop 0
	v_pk_add_f32 v[56:57], v[56:57], v[58:59]
	s_nop 0
	v_add_f32_e32 v56, v56, v57
	s_branch .LBB0_338

; __device__ __forceinline__ unsigned cvt_pk_bf16(float lo, float hi) { f32x2 v = {lo, hi}; return __builtin_bit_cast(unsigned, __builtin_convertvector(v, bf2_t)); }
;     __device__ __forceinline__ void operator()(const f32x4 (&acc)[2][2][4][2], const Unit& u, int wr, int wc, int fr, int fq) const {
;     ...
;             for (int m = 0; m < 4; ++m) {
;                 const int row = row0 + ai * HALF + m * 16;
;                 const size_t off = (size_t)row * 2048 + col0;
;                 float sq = 0.f;
; #pragma unroll
;                 for (int bj = 0; bj < 2; ++bj) {
;                     const u32x4 w = raw[m][bj];
;                     const f32x4 r0 = {__uint_as_float(w.x << 16), __uint_as_float(w.x & 0xffff0000u), __uint_as_float(w.y << 16), __uint_as_float(w.y & 0xffff0000u)};
;                     const f32x4 r1 = {__uint_as_float(w.z << 16), __uint_as_float(w.z & 0xffff0000u), __uint_as_float(w.w << 16), __uint_as_float(w.w & 0xffff0000u)};
;                     const f32x4 v0 = r0 + acc[ai][bj][m][0], v1 = r1 + acc[ai][bj][m][1];
;                     if (out32) { *(f32x4*)(out32 + off + bj * HALF) = v0; *(f32x4*)(out32 + off + bj * HALF + 4) = v1; }
;                     if (XB) { u32x4 o; o.x = cvt_pk_bf16(v0[0], v0[1]); o.y = cvt_pk_bf16(v0[2], v0[3]); o.z = cvt_pk_bf16(v1[0], v1[1]); o.w = cvt_pk_bf16(v1[2], v1[3]);
;                               *(u32x4*)(XB + off + bj * HALF) = o;
;                               sq += ((v0[0] * v0[0] + v0[1] * v0[1]) + (v0[2] * v0[2] + v0[3] * v0[3])) + ((v1[0] * v1[0] + v1[1] * v1[1]) + (v1[2] * v1[2] + v1[3] * v1[3])); }
;                 }
;                 if (XB) { sq += __shfl_xor(sq, 16); sq += __shfl_xor(sq, 32); if (fq == 0) SS[(size_t)row * 32 + u.pn * 4 + wc] = sq; }
;             }
.LBB0_338:
	v_lshlrev_b32_e32 v58, 16, v88
	v_and_b32_e32 v59, 0xffff0000, v88
	v_lshlrev_b32_e32 v60, 16, v89
	v_and_b32_e32 v61, 0xffff0000, v89
	v_lshlrev_b32_e32 v62, 16, v90
	v_and_b32_e32 v63, 0xffff0000, v90
	v_lshlrev_b32_e32 v88, 16, v91
	v_and_b32_e32 v89, 0xffff0000, v91
	v_pk_add_f32 v[54:55], v[54:55], v[60:61]
	v_pk_add_f32 v[52:53], v[52:53], v[58:59]
	v_pk_add_f32 v[50:51], v[50:51], v[88:89]
	v_pk_add_f32 v[48:49], v[48:49], v[62:63]
	v_cvt_pk_bf16_f32 v58, v52, v53
	v_cvt_pk_bf16_f32 v59, v54, v55
	v_cvt_pk_bf16_f32 v60, v48, v49
	v_cvt_pk_bf16_f32 v61, v50, v51
	s_and_b64 vcc, exec, s[6:7]
	global_store_dwordx4 v[100:101], v[58:61], off offset:256
	s_cbranch_vccnz .LBB0_342
	v_mul_f32_e32 v49, v49, v49
	v_mul_f32_e32 v53, v53, v53
	v_fmac_f32_e32 v49, v48, v48
	v_mul_f32_e32 v48, v51, v51
	v_fmac_f32_e32 v53, v52, v52
	v_mul_f32_e32 v52, v55, v55
	v_fmac_f32_e32 v48, v50, v50
	v_and_b32_e32 v50, 64, v184
	v_fmac_f32_e32 v52, v54, v54
	v_add_f32_e32 v48, v49, v48
	v_xor_b32_e32 v49, 16, v184
	v_add_u32_e32 v50, 64, v50
	v_add_f32_e32 v52, v53, v52
	v_cmp_lt_i32_e32 vcc, v49, v50
	v_add_f32_e32 v48, v52, v48
	v_add_f32_e32 v48, v48, v56
	v_cndmask_b32_e32 v49, v184, v49, vcc
	v_lshlrev_b32_e32 v49, 2, v49
	ds_bpermute_b32 v49, v49, v48
	s_waitcnt lgkmcnt(0)
	v_add_f32_e32 v48, v48, v49
	v_xor_b32_e32 v49, 32, v184
	v_cmp_lt_i32_e32 vcc, v49, v50
	s_nop 1
	v_cndmask_b32_e32 v49, v184, v49, vcc
	v_lshlrev_b32_e32 v49, 2, v49
	ds_bpermute_b32 v49, v49, v48
	s_and_saveexec_b64 s[28:29], s[2:3]
	s_cbranch_execz .LBB0_341
	v_readlane_b32 s30, v254, 57
	v_lshlrev_b64 v[50:51], 7, v[98:99]
	v_readlane_b32 s31, v254, 58
	s_lshl_b32 s8, s43, 2
	s_waitcnt lgkmcnt(0)
	v_add_f32_e32 v48, v48, v49
	v_lshl_add_u64 v[50:51], s[30:31], 0, v[50:51]
	v_lshl_add_u64 v[50:51], s[26:27], 2, v[50:51]
	v_lshl_add_u64 v[50:51], v[50:51], 0, s[8:9]
	global_store_dword v[50:51], v48, off

; __device__ __forceinline__ unsigned cvt_pk_bf16(float lo, float hi) { f32x2 v = {lo, hi}; return __builtin_bit_cast(unsigned, __builtin_convertvector(v, bf2_t)); }
;     __device__ __forceinline__ void operator()(const f32x4 (&acc)[2][2][4][2], const Unit& u, int wr, int wc, int fr, int fq) const {
;     ...
;             for (int m = 0; m < 4; ++m) {
;                 const int row = row0 + ai * HALF + m * 16;
;                 const size_t off = (size_t)row * 2048 + col0;
;                 float sq = 0.f;
; #pragma unroll
;                 for (int bj = 0; bj < 2; ++bj) {
;                     const u32x4 w = raw[m][bj];
;                     const f32x4 r0 = {__uint_as_float(w.x << 16), __uint_as_float(w.x & 0xffff0000u), __uint_as_float(w.y << 16), __uint_as_float(w.y & 0xffff0000u)};
;                     const f32x4 r1 = {__uint_as_float(w.z << 16), __uint_as_float(w.z & 0xffff0000u), __uint_as_float(w.w << 16), __uint_as_float(w.w & 0xffff0000u)};
;                     const f32x4 v0 = r0 + acc[ai][bj][m][0], v1 = r1 + acc[ai][bj][m][1];
;                     if (out32) { *(f32x4*)(out32 + off + bj * HALF) = v0; *(f32x4*)(out32 + off + bj * HALF + 4) = v1; }
;                     if (XB) { u32x4 o; o.x = cvt_pk_bf16(v0[0], v0[1]); o.y = cvt_pk_bf16(v0[2], v0[3]); o.z = cvt_pk_bf16(v1[0], v1[1]); o.w = cvt_pk_bf16(v1[2], v1[3]);
;                               *(u32x4*)(XB + off + bj * HALF) = o;
;                               sq += ((v0[0] * v0[0] + v0[1] * v0[1]) + (v0[2] * v0[2] + v0[3] * v0[3])) + ((v1[0] * v1[0] + v1[1] * v1[1]) + (v1[2] * v1[2] + v1[3] * v1[3])); }
;                 }
;                 if (XB) { sq += __shfl_xor(sq, 16); sq += __shfl_xor(sq, 32); if (fq == 0) SS[(size_t)row * 32 + u.pn * 4 + wc] = sq; }
;             }
.LBB0_342:
	s_waitcnt lgkmcnt(0)
	v_lshlrev_b64 v[48:49], 11, v[96:97]
	s_and_b64 vcc, exec, s[6:7]
	v_lshl_add_u64 v[48:49], v[48:49], 1, v[168:169]
	s_cbranch_vccnz .LBB0_344
	v_lshlrev_b32_e32 v50, 16, v86
	v_and_b32_e32 v51, 0xffff0000, v86
	v_lshlrev_b32_e32 v52, 16, v87
	v_and_b32_e32 v53, 0xffff0000, v87
	v_pk_add_f32 v[46:47], v[46:47], v[52:53]
	v_pk_add_f32 v[44:45], v[44:45], v[50:51]
	v_lshlrev_b32_e32 v50, 16, v84
	v_and_b32_e32 v51, 0xffff0000, v84
	v_lshlrev_b32_e32 v52, 16, v85
	v_and_b32_e32 v53, 0xffff0000, v85
	v_pk_add_f32 v[52:53], v[42:43], v[52:53]
	v_pk_add_f32 v[50:51], v[40:41], v[50:51]
	v_cvt_pk_bf16_f32 v41, v52, v53
	v_cvt_pk_bf16_f32 v40, v50, v51
	v_cvt_pk_bf16_f32 v42, v44, v45
	v_cvt_pk_bf16_f32 v43, v46, v47
	global_store_dwordx4 v[48:49], v[40:43], off
	s_nop 1
	v_mov_b32_e32 v41, v44
	v_mov_b32_e32 v44, v51
	v_mov_b32_e32 v40, v50
	v_pk_mul_f32 v[42:43], v[44:45], v[44:45]
	s_nop 0
	v_pk_fma_f32 v[40:41], v[40:41], v[40:41], v[42:43]
	v_mov_b32_e32 v43, v46
	v_mov_b32_e32 v46, v53
	v_mov_b32_e32 v42, v52
	v_pk_mul_f32 v[44:45], v[46:47], v[46:47]
	s_nop 0
	v_pk_fma_f32 v[42:43], v[42:43], v[42:43], v[44:45]
	s_nop 0
	v_pk_add_f32 v[40:41], v[40:41], v[42:43]
	s_nop 0
	v_add_f32_e32 v40, v40, v41
	s_branch .LBB0_345

; __device__ __forceinline__ unsigned cvt_pk_bf16(float lo, float hi) { f32x2 v = {lo, hi}; return __builtin_bit_cast(unsigned, __builtin_convertvector(v, bf2_t)); }
;     __device__ __forceinline__ void operator()(const f32x4 (&acc)[2][2][4][2], const Unit& u, int wr, int wc, int fr, int fq) const {
;     ...
;             for (int m = 0; m < 4; ++m) {
;                 const int row = row0 + ai * HALF + m * 16;
;                 const size_t off = (size_t)row * 2048 + col0;
;                 float sq = 0.f;
; #pragma unroll
;                 for (int bj = 0; bj < 2; ++bj) {
;                     const u32x4 w = raw[m][bj];
;                     const f32x4 r0 = {__uint_as_float(w.x << 16), __uint_as_float(w.x & 0xffff0000u), __uint_as_float(w.y << 16), __uint_as_float(w.y & 0xffff0000u)};
;                     const f32x4 r1 = {__uint_as_float(w.z << 16), __uint_as_float(w.z & 0xffff0000u), __uint_as_float(w.w << 16), __uint_as_float(w.w & 0xffff0000u)};
;                     const f32x4 v0 = r0 + acc[ai][bj][m][0], v1 = r1 + acc[ai][bj][m][1];
;                     if (out32) { *(f32x4*)(out32 + off + bj * HALF) = v0; *(f32x4*)(out32 + off + bj * HALF + 4) = v1; }
;                     if (XB) { u32x4 o; o.x = cvt_pk_bf16(v0[0], v0[1]); o.y = cvt_pk_bf16(v0[2], v0[3]); o.z = cvt_pk_bf16(v1[0], v1[1]); o.w = cvt_pk_bf16(v1[2], v1[3]);
;                               *(u32x4*)(XB + off + bj * HALF) = o;
;                               sq += ((v0[0] * v0[0] + v0[1] * v0[1]) + (v0[2] * v0[2] + v0[3] * v0[3])) + ((v1[0] * v1[0] + v1[1] * v1[1]) + (v1[2] * v1[2] + v1[3] * v1[3])); }
;                 }
;                 if (XB) { sq += __shfl_xor(sq, 16); sq += __shfl_xor(sq, 32); if (fq == 0) SS[(size_t)row * 32 + u.pn * 4 + wc] = sq; }
;             }
.LBB0_345:
	v_lshlrev_b32_e32 v42, 16, v80
	v_and_b32_e32 v43, 0xffff0000, v80
	v_lshlrev_b32_e32 v44, 16, v81
	v_and_b32_e32 v45, 0xffff0000, v81
	v_lshlrev_b32_e32 v46, 16, v82
	v_and_b32_e32 v47, 0xffff0000, v82
	v_lshlrev_b32_e32 v50, 16, v83
	v_and_b32_e32 v51, 0xffff0000, v83
	v_pk_add_f32 v[38:39], v[38:39], v[44:45]
	v_pk_add_f32 v[36:37], v[36:37], v[42:43]
	v_pk_add_f32 v[34:35], v[34:35], v[50:51]
	v_pk_add_f32 v[32:33], v[32:33], v[46:47]
	v_cvt_pk_bf16_f32 v42, v36, v37
	v_cvt_pk_bf16_f32 v43, v38, v39
	v_cvt_pk_bf16_f32 v44, v32, v33
	v_cvt_pk_bf16_f32 v45, v34, v35
	s_and_b64 vcc, exec, s[6:7]
	global_store_dwordx4 v[48:49], v[42:45], off offset:256
	s_cbranch_vccnz .LBB0_349
	v_mul_f32_e32 v33, v33, v33
	v_mul_f32_e32 v37, v37, v37
	v_fmac_f32_e32 v33, v32, v32
	v_mul_f32_e32 v32, v35, v35
	v_fmac_f32_e32 v37, v36, v36
	v_mul_f32_e32 v36, v39, v39
	v_fmac_f32_e32 v32, v34, v34
	v_and_b32_e32 v34, 64, v184
	v_fmac_f32_e32 v36, v38, v38
	v_add_f32_e32 v32, v33, v32
	v_xor_b32_e32 v33, 16, v184
	v_add_u32_e32 v34, 64, v34
	v_add_f32_e32 v36, v37, v36
	v_cmp_lt_i32_e32 vcc, v33, v34
	v_add_f32_e32 v32, v36, v32
	v_add_f32_e32 v32, v32, v40
	v_cndmask_b32_e32 v33, v184, v33, vcc
	v_lshlrev_b32_e32 v33, 2, v33
	ds_bpermute_b32 v33, v33, v32
	s_waitcnt lgkmcnt(0)
	v_add_f32_e32 v32, v32, v33
	v_xor_b32_e32 v33, 32, v184
	v_cmp_lt_i32_e32 vcc, v33, v34
	s_nop 1
	v_cndmask_b32_e32 v33, v184, v33, vcc
	v_lshlrev_b32_e32 v33, 2, v33
	ds_bpermute_b32 v33, v33, v32
	s_and_saveexec_b64 s[28:29], s[2:3]
	s_cbranch_execz .LBB0_348
	v_readlane_b32 s30, v254, 57
	v_lshlrev_b64 v[34:35], 7, v[96:97]
	v_readlane_b32 s31, v254, 58
	s_lshl_b32 s8, s43, 2
	s_waitcnt lgkmcnt(0)
	v_add_f32_e32 v32, v32, v33
	v_lshl_add_u64 v[34:35], s[30:31], 0, v[34:35]
	v_lshl_add_u64 v[34:35], s[26:27], 2, v[34:35]
	v_lshl_add_u64 v[34:35], v[34:35], 0, s[8:9]
	global_store_dword v[34:35], v32, off

; __device__ __forceinline__ unsigned cvt_pk_bf16(float lo, float hi) { f32x2 v = {lo, hi}; return __builtin_bit_cast(unsigned, __builtin_convertvector(v, bf2_t)); }
;     __device__ __forceinline__ void operator()(const f32x4 (&acc)[2][2][4][2], const Unit& u, int wr, int wc, int fr, int fq) const {
;     ...
;             for (int m = 0; m < 4; ++m) {
;                 const int row = row0 + ai * HALF + m * 16;
;                 const size_t off = (size_t)row * 2048 + col0;
;                 float sq = 0.f;
; #pragma unroll
;                 for (int bj = 0; bj < 2; ++bj) {
;                     const u32x4 w = raw[m][bj];
;                     const f32x4 r0 = {__uint_as_float(w.x << 16), __uint_as_float(w.x & 0xffff0000u), __uint_as_float(w.y << 16), __uint_as_float(w.y & 0xffff0000u)};
;                     const f32x4 r1 = {__uint_as_float(w.z << 16), __uint_as_float(w.z & 0xffff0000u), __uint_as_float(w.w << 16), __uint_as_float(w.w & 0xffff0000u)};
;                     const f32x4 v0 = r0 + acc[ai][bj][m][0], v1 = r1 + acc[ai][bj][m][1];
;                     if (out32) { *(f32x4*)(out32 + off + bj * HALF) = v0; *(f32x4*)(out32 + off + bj * HALF + 4) = v1; }
;                     if (XB) { u32x4 o; o.x = cvt_pk_bf16(v0[0], v0[1]); o.y = cvt_pk_bf16(v0[2], v0[3]); o.z = cvt_pk_bf16(v1[0], v1[1]); o.w = cvt_pk_bf16(v1[2], v1[3]);
;                               *(u32x4*)(XB + off + bj * HALF) = o;
;                               sq += ((v0[0] * v0[0] + v0[1] * v0[1]) + (v0[2] * v0[2] + v0[3] * v0[3])) + ((v1[0] * v1[0] + v1[1] * v1[1]) + (v1[2] * v1[2] + v1[3] * v1[3])); }
;                 }
;                 if (XB) { sq += __shfl_xor(sq, 16); sq += __shfl_xor(sq, 32); if (fq == 0) SS[(size_t)row * 32 + u.pn * 4 + wc] = sq; }
;             }
.LBB0_349:
	s_waitcnt lgkmcnt(0)
	v_lshlrev_b64 v[32:33], 11, v[94:95]
	s_and_b64 vcc, exec, s[6:7]
	v_lshl_add_u64 v[32:33], v[32:33], 1, v[168:169]
	s_cbranch_vccnz .LBB0_351
	v_lshlrev_b32_e32 v34, 16, v78
	v_and_b32_e32 v35, 0xffff0000, v78
	v_lshlrev_b32_e32 v36, 16, v79
	v_and_b32_e32 v37, 0xffff0000, v79
	v_pk_add_f32 v[30:31], v[30:31], v[36:37]
	v_pk_add_f32 v[28:29], v[28:29], v[34:35]
	v_lshlrev_b32_e32 v34, 16, v76
	v_and_b32_e32 v35, 0xffff0000, v76
	v_lshlrev_b32_e32 v36, 16, v77
	v_and_b32_e32 v37, 0xffff0000, v77
	v_pk_add_f32 v[36:37], v[26:27], v[36:37]
	v_pk_add_f32 v[34:35], v[24:25], v[34:35]
	v_cvt_pk_bf16_f32 v25, v36, v37
	v_cvt_pk_bf16_f32 v24, v34, v35
	v_cvt_pk_bf16_f32 v26, v28, v29
	v_cvt_pk_bf16_f32 v27, v30, v31
	global_store_dwordx4 v[32:33], v[24:27], off
	s_nop 1
	v_mov_b32_e32 v25, v28
	v_mov_b32_e32 v28, v35
	v_mov_b32_e32 v24, v34
	v_pk_mul_f32 v[26:27], v[28:29], v[28:29]
	s_nop 0
	v_pk_fma_f32 v[24:25], v[24:25], v[24:25], v[26:27]
	v_mov_b32_e32 v27, v30
	v_mov_b32_e32 v30, v37
	v_mov_b32_e32 v26, v36
	v_pk_mul_f32 v[28:29], v[30:31], v[30:31]
	s_nop 0
	v_pk_fma_f32 v[26:27], v[26:27], v[26:27], v[28:29]
	s_nop 0
	v_pk_add_f32 v[24:25], v[24:25], v[26:27]
	s_nop 0
	v_add_f32_e32 v24, v24, v25
	s_branch .LBB0_352

; __device__ __forceinline__ unsigned cvt_pk_bf16(float lo, float hi) { f32x2 v = {lo, hi}; return __builtin_bit_cast(unsigned, __builtin_convertvector(v, bf2_t)); }
;     __device__ __forceinline__ void operator()(const f32x4 (&acc)[2][2][4][2], const Unit& u, int wr, int wc, int fr, int fq) const {
;     ...
;             for (int m = 0; m < 4; ++m) {
;                 const int row = row0 + ai * HALF + m * 16;
;                 const size_t off = (size_t)row * 2048 + col0;
;                 float sq = 0.f;
; #pragma unroll
;                 for (int bj = 0; bj < 2; ++bj) {
;                     const u32x4 w = raw[m][bj];
;                     const f32x4 r0 = {__uint_as_float(w.x << 16), __uint_as_float(w.x & 0xffff0000u), __uint_as_float(w.y << 16), __uint_as_float(w.y & 0xffff0000u)};
;                     const f32x4 r1 = {__uint_as_float(w.z << 16), __uint_as_float(w.z & 0xffff0000u), __uint_as_float(w.w << 16), __uint_as_float(w.w & 0xffff0000u)};
;                     const f32x4 v0 = r0 + acc[ai][bj][m][0], v1 = r1 + acc[ai][bj][m][1];
;                     if (out32) { *(f32x4*)(out32 + off + bj * HALF) = v0; *(f32x4*)(out32 + off + bj * HALF + 4) = v1; }
;                     if (XB) { u32x4 o; o.x = cvt_pk_bf16(v0[0], v0[1]); o.y = cvt_pk_bf16(v0[2], v0[3]); o.z = cvt_pk_bf16(v1[0], v1[1]); o.w = cvt_pk_bf16(v1[2], v1[3]);
;                               *(u32x4*)(XB + off + bj * HALF) = o;
;                               sq += ((v0[0] * v0[0] + v0[1] * v0[1]) + (v0[2] * v0[2] + v0[3] * v0[3])) + ((v1[0] * v1[0] + v1[1] * v1[1]) + (v1[2] * v1[2] + v1[3] * v1[3])); }
;                 }
;                 if (XB) { sq += __shfl_xor(sq, 16); sq += __shfl_xor(sq, 32); if (fq == 0) SS[(size_t)row * 32 + u.pn * 4 + wc] = sq; }
;             }
.LBB0_352:
	v_lshlrev_b32_e32 v26, 16, v72
	v_and_b32_e32 v27, 0xffff0000, v72
	v_lshlrev_b32_e32 v28, 16, v73
	v_and_b32_e32 v29, 0xffff0000, v73
	v_lshlrev_b32_e32 v30, 16, v74
	v_and_b32_e32 v31, 0xffff0000, v74
	v_lshlrev_b32_e32 v34, 16, v75
	v_and_b32_e32 v35, 0xffff0000, v75
	v_pk_add_f32 v[22:23], v[22:23], v[28:29]
	v_pk_add_f32 v[20:21], v[20:21], v[26:27]
	v_pk_add_f32 v[18:19], v[18:19], v[34:35]
	v_pk_add_f32 v[16:17], v[16:17], v[30:31]
	v_cvt_pk_bf16_f32 v26, v20, v21
	v_cvt_pk_bf16_f32 v27, v22, v23
	v_cvt_pk_bf16_f32 v28, v16, v17
	v_cvt_pk_bf16_f32 v29, v18, v19
	s_and_b64 vcc, exec, s[6:7]
	global_store_dwordx4 v[32:33], v[26:29], off offset:256
	s_cbranch_vccnz .LBB0_356
	v_mul_f32_e32 v17, v17, v17
	v_mul_f32_e32 v21, v21, v21
	v_fmac_f32_e32 v17, v16, v16
	v_mul_f32_e32 v16, v19, v19
	v_fmac_f32_e32 v21, v20, v20
	v_mul_f32_e32 v20, v23, v23
	v_fmac_f32_e32 v16, v18, v18
	v_and_b32_e32 v18, 64, v184
	v_fmac_f32_e32 v20, v22, v22
	v_add_f32_e32 v16, v17, v16
	v_xor_b32_e32 v17, 16, v184
	v_add_u32_e32 v18, 64, v18
	v_add_f32_e32 v20, v21, v20
	v_cmp_lt_i32_e32 vcc, v17, v18
	v_add_f32_e32 v16, v20, v16
	v_add_f32_e32 v16, v16, v24
	v_cndmask_b32_e32 v17, v184, v17, vcc
	v_lshlrev_b32_e32 v17, 2, v17
	ds_bpermute_b32 v17, v17, v16
	s_waitcnt lgkmcnt(0)
	v_add_f32_e32 v16, v16, v17
	v_xor_b32_e32 v17, 32, v184
	v_cmp_lt_i32_e32 vcc, v17, v18
	s_nop 1
	v_cndmask_b32_e32 v17, v184, v17, vcc
	v_lshlrev_b32_e32 v17, 2, v17
	ds_bpermute_b32 v17, v17, v16
	s_and_saveexec_b64 s[28:29], s[2:3]
	s_cbranch_execz .LBB0_355
	v_readlane_b32 s30, v254, 57
	v_lshlrev_b64 v[18:19], 7, v[94:95]
	v_readlane_b32 s31, v254, 58
	s_lshl_b32 s8, s43, 2
	s_waitcnt lgkmcnt(0)
	v_add_f32_e32 v16, v16, v17
	v_lshl_add_u64 v[18:19], s[30:31], 0, v[18:19]
	v_lshl_add_u64 v[18:19], s[26:27], 2, v[18:19]
	v_lshl_add_u64 v[18:19], v[18:19], 0, s[8:9]
	global_store_dword v[18:19], v16, off

; __device__ __forceinline__ unsigned cvt_pk_bf16(float lo, float hi) { f32x2 v = {lo, hi}; return __builtin_bit_cast(unsigned, __builtin_convertvector(v, bf2_t)); }
;     __device__ __forceinline__ void operator()(const f32x4 (&acc)[2][2][4][2], const Unit& u, int wr, int wc, int fr, int fq) const {
;     ...
;             for (int m = 0; m < 4; ++m) {
;                 const int row = row0 + ai * HALF + m * 16;
;                 const size_t off = (size_t)row * 2048 + col0;
;                 float sq = 0.f;
; #pragma unroll
;                 for (int bj = 0; bj < 2; ++bj) {
;                     const u32x4 w = raw[m][bj];
;                     const f32x4 r0 = {__uint_as_float(w.x << 16), __uint_as_float(w.x & 0xffff0000u), __uint_as_float(w.y << 16), __uint_as_float(w.y & 0xffff0000u)};
;                     const f32x4 r1 = {__uint_as_float(w.z << 16), __uint_as_float(w.z & 0xffff0000u), __uint_as_float(w.w << 16), __uint_as_float(w.w & 0xffff0000u)};
;                     const f32x4 v0 = r0 + acc[ai][bj][m][0], v1 = r1 + acc[ai][bj][m][1];
;                     if (out32) { *(f32x4*)(out32 + off + bj * HALF) = v0; *(f32x4*)(out32 + off + bj * HALF + 4) = v1; }
;                     if (XB) { u32x4 o; o.x = cvt_pk_bf16(v0[0], v0[1]); o.y = cvt_pk_bf16(v0[2], v0[3]); o.z = cvt_pk_bf16(v1[0], v1[1]); o.w = cvt_pk_bf16(v1[2], v1[3]);
;                               *(u32x4*)(XB + off + bj * HALF) = o;
;                               sq += ((v0[0] * v0[0] + v0[1] * v0[1]) + (v0[2] * v0[2] + v0[3] * v0[3])) + ((v1[0] * v1[0] + v1[1] * v1[1]) + (v1[2] * v1[2] + v1[3] * v1[3])); }
;                 }
;                 if (XB) { sq += __shfl_xor(sq, 16); sq += __shfl_xor(sq, 32); if (fq == 0) SS[(size_t)row * 32 + u.pn * 4 + wc] = sq; }
;             }
.LBB0_356:
	s_waitcnt lgkmcnt(0)
	v_lshlrev_b64 v[16:17], 11, v[92:93]
	s_and_b64 vcc, exec, s[6:7]
	v_lshl_add_u64 v[16:17], v[16:17], 1, v[168:169]
	s_cbranch_vccnz .LBB0_358
	v_lshlrev_b32_e32 v18, 16, v70
	v_and_b32_e32 v19, 0xffff0000, v70
	v_lshlrev_b32_e32 v20, 16, v71
	v_and_b32_e32 v21, 0xffff0000, v71
	v_pk_add_f32 v[14:15], v[14:15], v[20:21]
	v_pk_add_f32 v[12:13], v[12:13], v[18:19]
	v_lshlrev_b32_e32 v18, 16, v68
	v_and_b32_e32 v19, 0xffff0000, v68
	v_lshlrev_b32_e32 v20, 16, v69
	v_and_b32_e32 v21, 0xffff0000, v69
	v_pk_add_f32 v[20:21], v[10:11], v[20:21]
	v_pk_add_f32 v[18:19], v[8:9], v[18:19]
	v_cvt_pk_bf16_f32 v9, v20, v21
	v_cvt_pk_bf16_f32 v8, v18, v19
	v_cvt_pk_bf16_f32 v10, v12, v13
	v_cvt_pk_bf16_f32 v11, v14, v15
	global_store_dwordx4 v[16:17], v[8:11], off
	s_nop 1
	v_mov_b32_e32 v9, v12
	v_mov_b32_e32 v12, v19
	v_mov_b32_e32 v8, v18
	v_pk_mul_f32 v[10:11], v[12:13], v[12:13]
	s_nop 0
	v_pk_fma_f32 v[8:9], v[8:9], v[8:9], v[10:11]
	v_mov_b32_e32 v11, v14
	v_mov_b32_e32 v14, v21
	v_mov_b32_e32 v10, v20
	v_pk_mul_f32 v[12:13], v[14:15], v[14:15]
	s_nop 0
	v_pk_fma_f32 v[10:11], v[10:11], v[10:11], v[12:13]
	s_nop 0
	v_pk_add_f32 v[8:9], v[8:9], v[10:11]
	s_nop 0
	v_add_f32_e32 v8, v8, v9
	s_branch .LBB0_359

; __device__ __forceinline__ unsigned cvt_pk_bf16(float lo, float hi) { f32x2 v = {lo, hi}; return __builtin_bit_cast(unsigned, __builtin_convertvector(v, bf2_t)); }
;     __device__ __forceinline__ void operator()(const f32x4 (&acc)[2][2][4][2], const Unit& u, int wr, int wc, int fr, int fq) const {
;     ...
;             for (int m = 0; m < 4; ++m) {
;                 const int row = row0 + ai * HALF + m * 16;
;                 const size_t off = (size_t)row * 2048 + col0;
;                 float sq = 0.f;
; #pragma unroll
;                 for (int bj = 0; bj < 2; ++bj) {
;                     const u32x4 w = raw[m][bj];
;                     const f32x4 r0 = {__uint_as_float(w.x << 16), __uint_as_float(w.x & 0xffff0000u), __uint_as_float(w.y << 16), __uint_as_float(w.y & 0xffff0000u)};
;                     const f32x4 r1 = {__uint_as_float(w.z << 16), __uint_as_float(w.z & 0xffff0000u), __uint_as_float(w.w << 16), __uint_as_float(w.w & 0xffff0000u)};
;                     const f32x4 v0 = r0 + acc[ai][bj][m][0], v1 = r1 + acc[ai][bj][m][1];
;                     if (out32) { *(f32x4*)(out32 + off + bj * HALF) = v0; *(f32x4*)(out32 + off + bj * HALF + 4) = v1; }
;                     if (XB) { u32x4 o; o.x = cvt_pk_bf16(v0[0], v0[1]); o.y = cvt_pk_bf16(v0[2], v0[3]); o.z = cvt_pk_bf16(v1[0], v1[1]); o.w = cvt_pk_bf16(v1[2], v1[3]);
;                               *(u32x4*)(XB + off + bj * HALF) = o;
;                               sq += ((v0[0] * v0[0] + v0[1] * v0[1]) + (v0[2] * v0[2] + v0[3] * v0[3])) + ((v1[0] * v1[0] + v1[1] * v1[1]) + (v1[2] * v1[2] + v1[3] * v1[3])); }
;                 }
;                 if (XB) { sq += __shfl_xor(sq, 16); sq += __shfl_xor(sq, 32); if (fq == 0) SS[(size_t)row * 32 + u.pn * 4 + wc] = sq; }
;             }
.LBB0_359:
	v_lshlrev_b32_e32 v10, 16, v64
	v_and_b32_e32 v11, 0xffff0000, v64
	v_lshlrev_b32_e32 v12, 16, v65
	v_and_b32_e32 v13, 0xffff0000, v65
	v_lshlrev_b32_e32 v14, 16, v66
	v_and_b32_e32 v15, 0xffff0000, v66
	v_pk_add_f32 v[6:7], v[6:7], v[12:13]
	v_pk_add_f32 v[4:5], v[4:5], v[10:11]
	v_lshlrev_b32_e32 v18, 16, v67
	v_and_b32_e32 v19, 0xffff0000, v67
	v_pk_add_f32 v[12:13], v[0:1], v[14:15]
	v_mul_f32_e32 v0, v5, v5
	v_mul_f32_e32 v1, v7, v7
	v_pk_add_f32 v[10:11], v[2:3], v[18:19]
	v_fmac_f32_e32 v0, v4, v4
	v_fmac_f32_e32 v1, v6, v6
	v_add_f32_e32 v0, v0, v1
	v_mul_f32_e32 v1, v13, v13
	v_mul_f32_e32 v2, v11, v11
	v_fmac_f32_e32 v1, v12, v12
	v_fmac_f32_e32 v2, v10, v10
	v_add_f32_e32 v1, v1, v2
	v_and_b32_e32 v2, 64, v184
	v_add_f32_e32 v0, v0, v1
	v_xor_b32_e32 v1, 16, v184
	v_add_u32_e32 v3, 64, v2
	v_cmp_lt_i32_e32 vcc, v1, v3
	v_add_f32_e32 v0, v0, v8
	v_cvt_pk_bf16_f32 v2, v4, v5
	v_cndmask_b32_e32 v1, v184, v1, vcc
	v_lshlrev_b32_e32 v1, 2, v1
	ds_bpermute_b32 v1, v1, v0
	v_cvt_pk_bf16_f32 v4, v12, v13
	v_cvt_pk_bf16_f32 v5, v10, v11
	s_waitcnt lgkmcnt(0)
	v_add_f32_e32 v0, v0, v1
	v_xor_b32_e32 v1, 32, v184
	v_cmp_lt_i32_e32 vcc, v1, v3
	v_cvt_pk_bf16_f32 v3, v6, v7
	global_store_dwordx4 v[16:17], v[2:5], off offset:256
	v_cndmask_b32_e32 v1, v184, v1, vcc
	v_lshlrev_b32_e32 v1, 2, v1
	ds_bpermute_b32 v1, v1, v0
	s_and_saveexec_b64 s[6:7], s[2:3]
	s_cbranch_execz .LBB0_361
	v_readlane_b32 s28, v254, 57
	v_lshlrev_b64 v[2:3], 7, v[92:93]
	v_readlane_b32 s29, v254, 58
	s_lshl_b32 s8, s43, 2
	s_waitcnt lgkmcnt(0)
	v_add_f32_e32 v0, v0, v1
	v_lshl_add_u64 v[2:3], s[28:29], 0, v[2:3]
	v_lshl_add_u64 v[2:3], s[26:27], 2, v[2:3]
	v_lshl_add_u64 v[2:3], v[2:3], 0, s[8:9]
	global_store_dword v[2:3], v0, off

;     __device__ bool next(int i, pg8::Unit& u) const { const int cnt = (nwg - c + G - 1) / G; if (i >= reps * cnt) return false; return pg8::StaticOrder::next(i % cnt, u); }
; template <class Epi, class Sched, bool ALIGN_EPI = false, bool SP2 = false>
; __device__ __forceinline__ void gemm_phase(PG8_LAS unsigned char* lds, const Gemm g, const Sched& S, const Epi& E) {
;     ...
;         const bool has_next = S.next(ui + 1, nxt);
;         const char* nA = has_next ? (const char*)g.A + (size_t)nxt.pm * tstep : cA; const char* nB = has_next ? (const char*)g.Bt + (size_t)nxt.pn * tstep : cB;
;         for (int t = 0; t < nt; t += 2) {
;             const bool last = (t == nt - 2);
;             const char* a1 = cA + (size_t)(t + 1) * kstep;
;             const char* a2 = last ? nA : cA + (size_t)(t + 2) * kstep; const char* b2 = last ? nB : cB + (size_t)(t + 2) * kstep;
;     ...
; #pragma unroll
;         for (int a = 0; a < 2; ++a)
; #pragma unroll
;             for (int b = 0; b < 2; ++b)
; #pragma unroll
;                 for (int m = 0; m < 4; ++m)
; #pragma unroll
;                     for (int n = 0; n < 2; ++n) acc[a][b][m][n] = (f32x4){0.f, 0.f, 0.f, 0.f};
.LBB0_490:
	s_ashr_i32 s21, s20, 31
	s_lshl_b64 s[0:1], s[20:21], 20
	v_readlane_b32 s24, v254, 51
	v_readlane_b32 s25, v254, 52
	s_add_u32 s24, s24, s0
	s_addc_u32 s25, s25, s1
	s_and_b64 s[0:1], s[22:23], exec
	s_cselect_b32 s5, s25, s31
	s_cselect_b32 s21, s24, s30
	s_ashr_i32 s19, s18, 31
	s_lshl_b64 s[0:1], s[18:19], 20
	v_readlane_b32 s26, v254, 22
	v_readlane_b32 s27, v254, 23
	s_add_u32 s26, s26, s0
	s_addc_u32 s27, s27, s1
	s_and_b64 s[0:1], s[22:23], exec
	s_cselect_b32 s19, s27, s29
	s_cselect_b32 s33, s26, s28
	s_add_u32 s0, s30, 0x80080
	s_addc_u32 s1, s31, 0
	s_add_u32 s44, s28, 0x100
	v_mov_b64_e32 v[0:1], 0
	v_mov_b64_e32 v[2:3], 0
	v_mov_b64_e32 v[4:5], 0
	v_mov_b64_e32 v[6:7], 0
	v_mov_b64_e32 v[8:9], 0
	v_mov_b64_e32 v[10:11], 0
	v_mov_b64_e32 v[12:13], 0
	v_mov_b64_e32 v[14:15], 0
	v_mov_b64_e32 v[16:17], 0
	v_mov_b64_e32 v[18:19], 0
	v_mov_b64_e32 v[20:21], 0
	v_mov_b64_e32 v[22:23], 0
	v_mov_b64_e32 v[24:25], 0
	v_mov_b64_e32 v[26:27], 0
	v_mov_b64_e32 v[28:29], 0
	v_mov_b64_e32 v[30:31], 0
	v_mov_b64_e32 v[32:33], 0
	v_mov_b64_e32 v[34:35], 0
	v_mov_b64_e32 v[36:37], 0
	v_mov_b64_e32 v[38:39], 0
	v_mov_b64_e32 v[40:41], 0
	v_mov_b64_e32 v[42:43], 0
	v_mov_b64_e32 v[44:45], 0
	v_mov_b64_e32 v[46:47], 0
	v_mov_b64_e32 v[48:49], 0
	v_mov_b64_e32 v[50:51], 0
	v_mov_b64_e32 v[52:53], 0
	v_mov_b64_e32 v[54:55], 0
	v_mov_b64_e32 v[56:57], 0
	v_mov_b64_e32 v[58:59], 0
	v_mov_b64_e32 v[60:61], 0
	v_mov_b64_e32 v[62:63], 0
	v_mov_b64_e32 v[64:65], 0
	v_mov_b64_e32 v[66:67], 0
	v_mov_b64_e32 v[68:69], 0
	v_mov_b64_e32 v[70:71], 0
	v_mov_b64_e32 v[72:73], 0
	v_mov_b64_e32 v[74:75], 0
	v_mov_b64_e32 v[76:77], 0
	v_mov_b64_e32 v[78:79], 0
	v_mov_b64_e32 v[80:81], 0
	v_mov_b64_e32 v[82:83], 0
	v_mov_b64_e32 v[84:85], 0
	v_mov_b64_e32 v[86:87], 0
	v_mov_b64_e32 v[88:89], 0
	v_mov_b64_e32 v[90:91], 0
	v_mov_b64_e32 v[92:93], 0
	v_mov_b64_e32 v[94:95], 0
	v_mov_b64_e32 v[96:97], 0
	v_mov_b64_e32 v[98:99], 0
	v_mov_b64_e32 v[100:101], 0
	v_mov_b64_e32 v[102:103], 0
	v_mov_b64_e32 v[104:105], 0
	v_mov_b64_e32 v[106:107], 0
	v_mov_b64_e32 v[108:109], 0
	v_mov_b64_e32 v[110:111], 0
	v_mov_b64_e32 v[112:113], 0
	v_mov_b64_e32 v[114:115], 0
	v_mov_b64_e32 v[116:117], 0
	v_mov_b64_e32 v[118:119], 0
	v_mov_b64_e32 v[120:121], 0
	v_mov_b64_e32 v[122:123], 0
	v_mov_b64_e32 v[124:125], 0
	v_mov_b64_e32 v[126:127], 0
	s_addc_u32 s45, s29, 0
	s_mov_b32 s48, -2

;     __device__ bool next(int i, pg8::Unit& u) const { const int cnt = (nwg - c + G - 1) / G; if (i >= reps * cnt) return false; return pg8::StaticOrder::next(i % cnt, u); }
; template <class Epi, class Sched, bool ALIGN_EPI = false, bool SP2 = false>
; __device__ __forceinline__ void gemm_phase(PG8_LAS unsigned char* lds, const Gemm g, const Sched& S, const Epi& E) {
;     ...
;         const bool has_next = S.next(ui + 1, nxt);
;         const char* nA = has_next ? (const char*)g.A + (size_t)nxt.pm * tstep : cA; const char* nB = has_next ? (const char*)g.Bt + (size_t)nxt.pn * tstep : cB;
;         for (int t = 0; t < nt; t += 2) {
;             const bool last = (t == nt - 2);
;             const char* a1 = cA + (size_t)(t + 1) * kstep;
;             const char* a2 = last ? nA : cA + (size_t)(t + 2) * kstep; const char* b2 = last ? nB : cB + (size_t)(t + 2) * kstep;
;     ...
; #pragma unroll
;         for (int a = 0; a < 2; ++a)
; #pragma unroll
;             for (int b = 0; b < 2; ++b)
; #pragma unroll
;                 for (int m = 0; m < 4; ++m)
; #pragma unroll
;                     for (int n = 0; n < 2; ++n) acc[a][b][m][n] = (f32x4){0.f, 0.f, 0.f, 0.f};
.LBB0_762:
	s_ashr_i32 s21, s20, 31
	s_lshl_b64 s[22:23], s[20:21], 21
	s_add_u32 s22, s60, s22
	s_addc_u32 s23, s61, s23
	s_and_b64 s[24:25], s[4:5], exec
	s_cselect_b32 s7, s23, s27
	s_cselect_b32 s21, s22, s26
	s_ashr_i32 s19, s18, 31
	s_lshl_b64 s[24:25], s[18:19], 21
	v_readlane_b32 s30, v254, 32
	v_readlane_b32 s31, v254, 33
	s_add_u32 s24, s30, s24
	s_addc_u32 s25, s31, s25
	s_and_b64 s[30:31], s[4:5], exec
	s_cselect_b32 s19, s25, s29
	s_cselect_b32 s48, s24, s28
	s_add_u32 s26, s26, 0x100080
	s_addc_u32 s27, s27, 0
	s_add_u32 s49, s28, 0x100
	v_mov_b64_e32 v[0:1], 0
	v_mov_b64_e32 v[2:3], 0
	v_mov_b64_e32 v[4:5], 0
	v_mov_b64_e32 v[6:7], 0
	v_mov_b64_e32 v[8:9], 0
	v_mov_b64_e32 v[10:11], 0
	v_mov_b64_e32 v[12:13], 0
	v_mov_b64_e32 v[14:15], 0
	v_mov_b64_e32 v[16:17], 0
	v_mov_b64_e32 v[18:19], 0
	v_mov_b64_e32 v[20:21], 0
	v_mov_b64_e32 v[22:23], 0
	v_mov_b64_e32 v[24:25], 0
	v_mov_b64_e32 v[26:27], 0
	v_mov_b64_e32 v[28:29], 0
	v_mov_b64_e32 v[30:31], 0
	v_mov_b64_e32 v[32:33], 0
	v_mov_b64_e32 v[34:35], 0
	v_mov_b64_e32 v[36:37], 0
	v_mov_b64_e32 v[38:39], 0
	v_mov_b64_e32 v[40:41], 0
	v_mov_b64_e32 v[42:43], 0
	v_mov_b64_e32 v[44:45], 0
	v_mov_b64_e32 v[46:47], 0
	v_mov_b64_e32 v[48:49], 0
	v_mov_b64_e32 v[50:51], 0
	v_mov_b64_e32 v[52:53], 0
	v_mov_b64_e32 v[54:55], 0
	v_mov_b64_e32 v[56:57], 0
	v_mov_b64_e32 v[58:59], 0
	v_mov_b64_e32 v[60:61], 0
	v_mov_b64_e32 v[62:63], 0
	v_mov_b64_e32 v[64:65], 0
	v_mov_b64_e32 v[66:67], 0
	v_mov_b64_e32 v[68:69], 0
	v_mov_b64_e32 v[70:71], 0
	v_mov_b64_e32 v[72:73], 0
	v_mov_b64_e32 v[74:75], 0
	v_mov_b64_e32 v[76:77], 0
	v_mov_b64_e32 v[78:79], 0
	v_mov_b64_e32 v[80:81], 0
	v_mov_b64_e32 v[82:83], 0
	v_mov_b64_e32 v[84:85], 0
	v_mov_b64_e32 v[86:87], 0
	v_mov_b64_e32 v[88:89], 0
	v_mov_b64_e32 v[90:91], 0
	v_mov_b64_e32 v[92:93], 0
	v_mov_b64_e32 v[94:95], 0
	v_mov_b64_e32 v[96:97], 0
	v_mov_b64_e32 v[98:99], 0
	v_mov_b64_e32 v[100:101], 0
	v_mov_b64_e32 v[102:103], 0
	v_mov_b64_e32 v[104:105], 0
	v_mov_b64_e32 v[106:107], 0
	v_mov_b64_e32 v[108:109], 0
	v_mov_b64_e32 v[110:111], 0
	v_mov_b64_e32 v[112:113], 0
	v_mov_b64_e32 v[114:115], 0
	v_mov_b64_e32 v[116:117], 0
	v_mov_b64_e32 v[118:119], 0
	v_mov_b64_e32 v[120:121], 0
	v_mov_b64_e32 v[122:123], 0
	v_mov_b64_e32 v[124:125], 0
	v_mov_b64_e32 v[126:127], 0
	s_addc_u32 s52, s29, 0
	s_mov_b32 s53, -2
	s_waitcnt lgkmcnt(0)

; __device__ __forceinline__ unsigned cvt_pk_bf16(float lo, float hi) { f32x2 v = {lo, hi}; return __builtin_bit_cast(unsigned, __builtin_convertvector(v, bf2_t)); }
;     __device__ __forceinline__ void operator()(const f32x4 (&acc)[2][2][4][2], const Unit& u, int wr, int wc, int fr, int fq) const {
;         const int row0 = u.pm * BM + wr * 64 + fr, col0 = u.pn * BM + wc * 32 + 8 * fq;
; #pragma unroll
;         for (int ai = 0; ai < 2; ++ai) {
;             u32x4 raw[4][2];
; #pragma unroll
;             for (int m = 0; m < 4; ++m)
; #pragma unroll
;                 for (int bj = 0; bj < 2; ++bj) raw[m][bj] = *(const u32x4*)(base16 + (size_t)(row0 + ai * HALF + m * 16) * 2048 + col0 + bj * HALF);
; #pragma unroll
;             for (int m = 0; m < 4; ++m) {
;                 const int row = row0 + ai * HALF + m * 16;
;                 const size_t off = (size_t)row * 2048 + col0;
;                 float sq = 0.f;
; #pragma unroll
;                 for (int bj = 0; bj < 2; ++bj) {
;                     const u32x4 w = raw[m][bj];
;                     const f32x4 r0 = {__uint_as_float(w.x << 16), __uint_as_float(w.x & 0xffff0000u), __uint_as_float(w.y << 16), __uint_as_float(w.y & 0xffff0000u)};
;                     const f32x4 r1 = {__uint_as_float(w.z << 16), __uint_as_float(w.z & 0xffff0000u), __uint_as_float(w.w << 16), __uint_as_float(w.w & 0xffff0000u)};
;                     const f32x4 v0 = r0 + acc[ai][bj][m][0], v1 = r1 + acc[ai][bj][m][1];
;                     if (out32) { *(f32x4*)(out32 + off + bj * HALF) = v0; *(f32x4*)(out32 + off + bj * HALF + 4) = v1; }
;                     if (XB) { u32x4 o; o.x = cvt_pk_bf16(v0[0], v0[1]); o.y = cvt_pk_bf16(v0[2], v0[3]); o.z = cvt_pk_bf16(v1[0], v1[1]); o.w = cvt_pk_bf16(v1[2], v1[3]);
;                               *(u32x4*)(XB + off + bj * HALF) = o;
;                               sq += ((v0[0] * v0[0] + v0[1] * v0[1]) + (v0[2] * v0[2] + v0[3] * v0[3])) + ((v1[0] * v1[0] + v1[1] * v1[1]) + (v1[2] * v1[2] + v1[3] * v1[3])); }
;                 }
;                 if (XB) { sq += __shfl_xor(sq, 16); sq += __shfl_xor(sq, 32); if (fq == 0) SS[(size_t)row * 32 + u.pn * 4 + wc] = sq; }
;             }
.LBB0_766:
	v_lshl_or_b32 v128, s6, 8, v180
	v_lshl_add_u32 v170, s8, 8, v178
	v_ashrrev_i32_e32 v129, 31, v128
	v_lshlrev_b64 v[194:195], 1, v[128:129]
	v_ashrrev_i32_e32 v171, 31, v170
	v_lshl_add_u64 v[168:169], s[74:75], 0, v[194:195]
	v_lshlrev_b64 v[198:199], 12, v[170:171]
	v_or_b32_e32 v176, 16, v170
	v_or_b32_e32 v174, 32, v170
	v_lshl_add_u64 v[128:129], v[168:169], 0, v[198:199]
	v_or_b32_e32 v172, 48, v170
	v_ashrrev_i32_e32 v177, 31, v176
	v_ashrrev_i32_e32 v175, 31, v174
	global_load_dwordx4 v[186:189], v[128:129], off
	global_load_dwordx4 v[190:193], v[128:129], off offset:256
	v_ashrrev_i32_e32 v173, 31, v172
	v_lshlrev_b64 v[128:129], 12, v[176:177]
	v_lshlrev_b64 v[130:131], 12, v[174:175]
	v_lshlrev_b64 v[132:133], 12, v[172:173]
	v_lshl_add_u64 v[128:129], v[168:169], 0, v[128:129]
	v_lshl_add_u64 v[130:131], v[168:169], 0, v[130:131]
	v_lshl_add_u64 v[200:201], v[168:169], 0, v[132:133]
	global_load_dwordx4 v[148:151], v[128:129], off
	global_load_dwordx4 v[144:147], v[128:129], off offset:256
	global_load_dwordx4 v[140:143], v[130:131], off
	global_load_dwordx4 v[136:139], v[130:131], off offset:256
	global_load_dwordx4 v[132:135], v[200:201], off
	s_nop 0
	global_load_dwordx4 v[128:131], v[200:201], off offset:256
	v_lshl_add_u64 v[198:199], s[74:75], 0, v[198:199]
	v_lshl_add_u64 v[194:195], v[198:199], 0, v[194:195]
	s_lshl_b32 s26, s6, 2
	v_cndmask_b32_e64 v185, 0, 1, s[16:17]
	s_ashr_i32 s27, s26, 31
	v_cmp_ne_u32_e64 s[6:7], 1, v185
	s_andn2_b64 vcc, exec, s[16:17]
	v_add_u32_e32 v244, 0x80, v170
	v_ashrrev_i32_e32 v245, 31, v244
	v_lshlrev_b64 v[244:245], 12, v[244:245]
	v_lshl_add_u64 v[244:245], v[168:169], 0, v[244:245]
	global_load_dwordx4 v[206:209], v[244:245], off
	global_load_dwordx4 v[210:213], v[244:245], off offset:256
	v_add_u32_e32 v244, 0x90, v170
	v_ashrrev_i32_e32 v245, 31, v244
	v_lshlrev_b64 v[244:245], 12, v[244:245]
	v_lshl_add_u64 v[244:245], v[168:169], 0, v[244:245]
	global_load_dwordx4 v[214:217], v[244:245], off
	global_load_dwordx4 v[218:221], v[244:245], off offset:256
	v_add_u32_e32 v244, 0xa0, v170
	v_ashrrev_i32_e32 v245, 31, v244
	v_lshlrev_b64 v[244:245], 12, v[244:245]
	v_lshl_add_u64 v[244:245], v[168:169], 0, v[244:245]
	global_load_dwordx4 v[228:231], v[244:245], off
	global_load_dwordx4 v[232:235], v[244:245], off offset:256
	v_add_u32_e32 v244, 0xb0, v170
	v_ashrrev_i32_e32 v245, 31, v244
	v_lshlrev_b64 v[244:245], 12, v[244:245]
	v_lshl_add_u64 v[244:245], v[168:169], 0, v[244:245]
	global_load_dwordx4 v[236:239], v[244:245], off
	global_load_dwordx4 v[240:243], v[244:245], off offset:256
	s_waitcnt vmcnt(0)
	v_lshlrev_b32_e32 v198, 16, v186
	v_and_b32_e32 v199, 0xffff0000, v186
	v_lshlrev_b32_e32 v186, 16, v187
	v_and_b32_e32 v187, 0xffff0000, v187
	v_lshlrev_b32_e32 v200, 16, v188
	v_and_b32_e32 v201, 0xffff0000, v188
	v_lshlrev_b32_e32 v188, 16, v189
	v_and_b32_e32 v189, 0xffff0000, v189
	v_lshlrev_b32_e32 v202, 16, v190
	v_and_b32_e32 v203, 0xffff0000, v190
	v_lshlrev_b32_e32 v190, 16, v191
	v_and_b32_e32 v191, 0xffff0000, v191
	v_lshlrev_b32_e32 v204, 16, v192
	v_and_b32_e32 v205, 0xffff0000, v192
	v_lshlrev_b32_e32 v192, 16, v193
	v_and_b32_e32 v193, 0xffff0000, v193
	v_pk_add_f32 v[126:127], v[126:127], v[186:187]
	v_pk_add_f32 v[124:125], v[124:125], v[198:199]
	v_pk_add_f32 v[122:123], v[122:123], v[188:189]
	v_pk_add_f32 v[120:121], v[120:121], v[200:201]
	v_pk_add_f32 v[118:119], v[118:119], v[190:191]
	v_pk_add_f32 v[116:117], v[116:117], v[202:203]
	v_pk_add_f32 v[114:115], v[114:115], v[192:193]
	v_pk_add_f32 v[112:113], v[112:113], v[204:205]
	v_cvt_pk_bf16_f32 v186, v124, v125
	v_cvt_pk_bf16_f32 v187, v126, v127
	v_cvt_pk_bf16_f32 v188, v120, v121
	v_cvt_pk_bf16_f32 v189, v122, v123
	v_cvt_pk_bf16_f32 v190, v116, v117
	v_cvt_pk_bf16_f32 v191, v118, v119
	v_cvt_pk_bf16_f32 v192, v112, v113
	v_cvt_pk_bf16_f32 v193, v114, v115
	global_store_dwordx4 v[194:195], v[186:189], off
	global_store_dwordx4 v[194:195], v[190:193], off offset:256
	s_cbranch_vccnz .LBB0_770
	v_mul_f32_e32 v113, v113, v113
	v_mul_f32_e32 v125, v125, v125
	v_mul_f32_e32 v121, v121, v121
	v_mul_f32_e32 v117, v117, v117
	v_fmac_f32_e32 v113, v112, v112
	v_mul_f32_e32 v112, v115, v115
	v_fmac_f32_e32 v125, v124, v124
	v_mul_f32_e32 v124, v127, v127
	v_fmac_f32_e32 v121, v120, v120
	v_mul_f32_e32 v120, v123, v123
	v_fmac_f32_e32 v117, v116, v116
	v_mul_f32_e32 v116, v119, v119
	v_fmac_f32_e32 v112, v114, v114
	v_and_b32_e32 v114, 64, v184
	v_fmac_f32_e32 v124, v126, v126
	v_fmac_f32_e32 v120, v122, v122
	v_fmac_f32_e32 v116, v118, v118
	v_add_f32_e32 v112, v113, v112
	v_xor_b32_e32 v113, 16, v184
	v_add_u32_e32 v114, 64, v114
	v_add_f32_e32 v124, v125, v124
	v_add_f32_e32 v120, v121, v120
	v_add_f32_e32 v116, v117, v116
	v_cmp_lt_i32_e32 vcc, v113, v114
	v_add_f32_e32 v120, v124, v120
	v_add_f32_e32 v112, v116, v112
	v_cndmask_b32_e32 v113, v184, v113, vcc
	v_add_f32_e32 v112, v120, v112
	v_lshlrev_b32_e32 v113, 2, v113
	ds_bpermute_b32 v113, v113, v112
	s_waitcnt lgkmcnt(0)
	v_add_f32_e32 v112, v112, v113
	v_xor_b32_e32 v113, 32, v184
	v_cmp_lt_i32_e32 vcc, v113, v114
	s_nop 1
	v_cndmask_b32_e32 v113, v184, v113, vcc
	v_lshlrev_b32_e32 v113, 2, v113
	ds_bpermute_b32 v113, v113, v112
	s_and_saveexec_b64 s[28:29], s[2:3]
	s_cbranch_execz .LBB0_769
	v_lshlrev_b64 v[114:115], 7, v[170:171]
	v_lshl_add_u64 v[114:115], s[64:65], 0, v[114:115]
	v_lshl_add_u64 v[114:115], s[26:27], 2, v[114:115]
	s_lshl_b32 s8, s42, 2
	v_lshl_add_u64 v[114:115], v[114:115], 0, s[8:9]
	s_waitcnt lgkmcnt(0)
	v_add_f32_e32 v112, v112, v113
	global_store_dword v[114:115], v112, off

; __device__ __forceinline__ unsigned cvt_pk_bf16(float lo, float hi) { f32x2 v = {lo, hi}; return __builtin_bit_cast(unsigned, __builtin_convertvector(v, bf2_t)); }
;     __device__ __forceinline__ void operator()(const f32x4 (&acc)[2][2][4][2], const Unit& u, int wr, int wc, int fr, int fq) const {
;     ...
;         for (int ai = 0; ai < 2; ++ai) {
;             u32x4 raw[4][2];
; #pragma unroll
;             for (int m = 0; m < 4; ++m)
; #pragma unroll
;                 for (int bj = 0; bj < 2; ++bj) raw[m][bj] = *(const u32x4*)(base16 + (size_t)(row0 + ai * HALF + m * 16) * 2048 + col0 + bj * HALF);
; #pragma unroll
;             for (int m = 0; m < 4; ++m) {
;                 const int row = row0 + ai * HALF + m * 16;
;                 const size_t off = (size_t)row * 2048 + col0;
;                 float sq = 0.f;
; #pragma unroll
;                 for (int bj = 0; bj < 2; ++bj) {
;                     const u32x4 w = raw[m][bj];
;                     const f32x4 r0 = {__uint_as_float(w.x << 16), __uint_as_float(w.x & 0xffff0000u), __uint_as_float(w.y << 16), __uint_as_float(w.y & 0xffff0000u)};
;                     const f32x4 r1 = {__uint_as_float(w.z << 16), __uint_as_float(w.z & 0xffff0000u), __uint_as_float(w.w << 16), __uint_as_float(w.w & 0xffff0000u)};
;                     const f32x4 v0 = r0 + acc[ai][bj][m][0], v1 = r1 + acc[ai][bj][m][1];
;                     if (out32) { *(f32x4*)(out32 + off + bj * HALF) = v0; *(f32x4*)(out32 + off + bj * HALF + 4) = v1; }
;                     if (XB) { u32x4 o; o.x = cvt_pk_bf16(v0[0], v0[1]); o.y = cvt_pk_bf16(v0[2], v0[3]); o.z = cvt_pk_bf16(v1[0], v1[1]); o.w = cvt_pk_bf16(v1[2], v1[3]);
;                               *(u32x4*)(XB + off + bj * HALF) = o;
;                               sq += ((v0[0] * v0[0] + v0[1] * v0[1]) + (v0[2] * v0[2] + v0[3] * v0[3])) + ((v1[0] * v1[0] + v1[1] * v1[1]) + (v1[2] * v1[2] + v1[3] * v1[3])); }
;                 }
;                 if (XB) { sq += __shfl_xor(sq, 16); sq += __shfl_xor(sq, 32); if (fq == 0) SS[(size_t)row * 32 + u.pn * 4 + wc] = sq; }
;             }
.LBB0_791:
	v_add_u32_e32 v98, 0x80, v170
	v_ashrrev_i32_e32 v99, 31, v98
	v_add_u32_e32 v96, 0x90, v170
	s_waitcnt lgkmcnt(0)
	v_lshlrev_b64 v[64:65], 12, v[98:99]
	v_ashrrev_i32_e32 v97, 31, v96
	v_add_u32_e32 v94, 0xa0, v170
	v_lshl_add_u64 v[102:103], v[168:169], 0, v[64:65]
	v_lshlrev_b64 v[64:65], 12, v[96:97]
	v_ashrrev_i32_e32 v95, 31, v94
	v_add_u32_e32 v92, 0xb0, v170
	v_lshl_add_u64 v[64:65], v[168:169], 0, v[64:65]
	v_lshlrev_b64 v[66:67], 12, v[94:95]
	v_ashrrev_i32_e32 v93, 31, v92
	v_mov_b64_e32 v[88:89], v[210:211]
	v_mov_b64_e32 v[90:91], v[212:213]
	v_mov_b64_e32 v[84:85], v[214:215]
	v_mov_b64_e32 v[86:87], v[216:217]
	v_lshl_add_u64 v[66:67], v[168:169], 0, v[66:67]
	v_mov_b64_e32 v[80:81], v[218:219]
	v_mov_b64_e32 v[82:83], v[220:221]
	v_mov_b64_e32 v[76:77], v[228:229]
	v_mov_b64_e32 v[78:79], v[230:231]
	v_lshlrev_b64 v[64:65], 12, v[92:93]
	v_lshl_add_u64 v[64:65], v[168:169], 0, v[64:65]
	v_mov_b64_e32 v[72:73], v[232:233]
	v_mov_b64_e32 v[74:75], v[234:235]
	v_mov_b64_e32 v[68:69], v[236:237]
	v_mov_b64_e32 v[70:71], v[238:239]
	v_mov_b64_e32 v[64:65], v[240:241]
	v_mov_b64_e32 v[66:67], v[242:243]
	v_lshlrev_b64 v[100:101], 11, v[98:99]
	s_and_b64 vcc, exec, s[6:7]
	v_lshl_add_u64 v[100:101], v[100:101], 1, v[168:169]
	s_cbranch_vccnz .LBB0_793
	v_mov_b64_e32 v[102:103], v[206:207]
	v_mov_b64_e32 v[104:105], v[208:209]
	v_lshlrev_b32_e32 v106, 16, v104
	v_and_b32_e32 v107, 0xffff0000, v104
	v_lshlrev_b32_e32 v104, 16, v105
	v_and_b32_e32 v105, 0xffff0000, v105
	v_lshlrev_b32_e32 v108, 16, v102
	v_and_b32_e32 v109, 0xffff0000, v102
	v_lshlrev_b32_e32 v102, 16, v103
	v_and_b32_e32 v103, 0xffff0000, v103
	v_pk_add_f32 v[62:63], v[62:63], v[104:105]
	v_pk_add_f32 v[60:61], v[60:61], v[106:107]
	v_pk_add_f32 v[102:103], v[58:59], v[102:103]
	v_pk_add_f32 v[104:105], v[56:57], v[108:109]
	v_cvt_pk_bf16_f32 v57, v102, v103
	v_cvt_pk_bf16_f32 v56, v104, v105
	v_cvt_pk_bf16_f32 v58, v60, v61
	v_cvt_pk_bf16_f32 v59, v62, v63
	v_mov_b32_e32 v107, v60
	v_mov_b32_e32 v60, v105
	v_mov_b32_e32 v105, v62
	v_mov_b32_e32 v62, v103
	v_mov_b32_e32 v106, v104
	v_mov_b32_e32 v104, v102
	global_store_dwordx4 v[100:101], v[56:59], off
	s_nop 1
	v_pk_mul_f32 v[56:57], v[60:61], v[60:61]
	v_pk_mul_f32 v[58:59], v[62:63], v[62:63]
	v_pk_fma_f32 v[56:57], v[106:107], v[106:107], v[56:57]
	v_pk_fma_f32 v[58:59], v[104:105], v[104:105], v[58:59]
	s_nop 0
	v_pk_add_f32 v[56:57], v[56:57], v[58:59]
	s_nop 0
	v_add_f32_e32 v56, v56, v57
	s_branch .LBB0_794

; __device__ __forceinline__ unsigned cvt_pk_bf16(float lo, float hi) { f32x2 v = {lo, hi}; return __builtin_bit_cast(unsigned, __builtin_convertvector(v, bf2_t)); }
;     __device__ __forceinline__ void operator()(const f32x4 (&acc)[2][2][4][2], const Unit& u, int wr, int wc, int fr, int fq) const {
;     ...
;             for (int m = 0; m < 4; ++m) {
;                 const int row = row0 + ai * HALF + m * 16;
;                 const size_t off = (size_t)row * 2048 + col0;
;                 float sq = 0.f;
; #pragma unroll
;                 for (int bj = 0; bj < 2; ++bj) {
;                     const u32x4 w = raw[m][bj];
;                     const f32x4 r0 = {__uint_as_float(w.x << 16), __uint_as_float(w.x & 0xffff0000u), __uint_as_float(w.y << 16), __uint_as_float(w.y & 0xffff0000u)};
;                     const f32x4 r1 = {__uint_as_float(w.z << 16), __uint_as_float(w.z & 0xffff0000u), __uint_as_float(w.w << 16), __uint_as_float(w.w & 0xffff0000u)};
;                     const f32x4 v0 = r0 + acc[ai][bj][m][0], v1 = r1 + acc[ai][bj][m][1];
;                     if (out32) { *(f32x4*)(out32 + off + bj * HALF) = v0; *(f32x4*)(out32 + off + bj * HALF + 4) = v1; }
;                     if (XB) { u32x4 o; o.x = cvt_pk_bf16(v0[0], v0[1]); o.y = cvt_pk_bf16(v0[2], v0[3]); o.z = cvt_pk_bf16(v1[0], v1[1]); o.w = cvt_pk_bf16(v1[2], v1[3]);
;                               *(u32x4*)(XB + off + bj * HALF) = o;
;                               sq += ((v0[0] * v0[0] + v0[1] * v0[1]) + (v0[2] * v0[2] + v0[3] * v0[3])) + ((v1[0] * v1[0] + v1[1] * v1[1]) + (v1[2] * v1[2] + v1[3] * v1[3])); }
;                 }
;                 if (XB) { sq += __shfl_xor(sq, 16); sq += __shfl_xor(sq, 32); if (fq == 0) SS[(size_t)row * 32 + u.pn * 4 + wc] = sq; }
;             }
.LBB0_794:
	v_lshlrev_b32_e32 v58, 16, v88
	v_and_b32_e32 v59, 0xffff0000, v88
	v_lshlrev_b32_e32 v60, 16, v89
	v_and_b32_e32 v61, 0xffff0000, v89
	v_lshlrev_b32_e32 v62, 16, v90
	v_and_b32_e32 v63, 0xffff0000, v90
	v_lshlrev_b32_e32 v88, 16, v91
	v_and_b32_e32 v89, 0xffff0000, v91
	v_pk_add_f32 v[54:55], v[54:55], v[60:61]
	v_pk_add_f32 v[52:53], v[52:53], v[58:59]
	v_pk_add_f32 v[50:51], v[50:51], v[88:89]
	v_pk_add_f32 v[48:49], v[48:49], v[62:63]
	v_cvt_pk_bf16_f32 v58, v52, v53
	v_cvt_pk_bf16_f32 v59, v54, v55
	v_cvt_pk_bf16_f32 v60, v48, v49
	v_cvt_pk_bf16_f32 v61, v50, v51
	s_and_b64 vcc, exec, s[6:7]
	global_store_dwordx4 v[100:101], v[58:61], off offset:256
	s_cbranch_vccnz .LBB0_798
	v_mul_f32_e32 v49, v49, v49
	v_mul_f32_e32 v53, v53, v53
	v_fmac_f32_e32 v49, v48, v48
	v_mul_f32_e32 v48, v51, v51
	v_fmac_f32_e32 v53, v52, v52
	v_mul_f32_e32 v52, v55, v55
	v_fmac_f32_e32 v48, v50, v50
	v_and_b32_e32 v50, 64, v184
	v_fmac_f32_e32 v52, v54, v54
	v_add_f32_e32 v48, v49, v48
	v_xor_b32_e32 v49, 16, v184
	v_add_u32_e32 v50, 64, v50
	v_add_f32_e32 v52, v53, v52
	v_cmp_lt_i32_e32 vcc, v49, v50
	v_add_f32_e32 v48, v52, v48
	v_add_f32_e32 v48, v48, v56
	v_cndmask_b32_e32 v49, v184, v49, vcc
	v_lshlrev_b32_e32 v49, 2, v49
	ds_bpermute_b32 v49, v49, v48
	s_waitcnt lgkmcnt(0)
	v_add_f32_e32 v48, v48, v49
	v_xor_b32_e32 v49, 32, v184
	v_cmp_lt_i32_e32 vcc, v49, v50
	s_nop 1
	v_cndmask_b32_e32 v49, v184, v49, vcc
	v_lshlrev_b32_e32 v49, 2, v49
	ds_bpermute_b32 v49, v49, v48
	s_and_saveexec_b64 s[28:29], s[2:3]
	s_cbranch_execz .LBB0_797
	v_lshlrev_b64 v[50:51], 7, v[98:99]
	v_lshl_add_u64 v[50:51], s[64:65], 0, v[50:51]
	v_lshl_add_u64 v[50:51], s[26:27], 2, v[50:51]
	s_lshl_b32 s8, s42, 2
	v_lshl_add_u64 v[50:51], v[50:51], 0, s[8:9]
	s_waitcnt lgkmcnt(0)
	v_add_f32_e32 v48, v48, v49
	global_store_dword v[50:51], v48, off

; __device__ __forceinline__ unsigned cvt_pk_bf16(float lo, float hi) { f32x2 v = {lo, hi}; return __builtin_bit_cast(unsigned, __builtin_convertvector(v, bf2_t)); }
;     __device__ __forceinline__ void operator()(const f32x4 (&acc)[2][2][4][2], const Unit& u, int wr, int wc, int fr, int fq) const {
;     ...
;             for (int m = 0; m < 4; ++m) {
;                 const int row = row0 + ai * HALF + m * 16;
;                 const size_t off = (size_t)row * 2048 + col0;
;                 float sq = 0.f;
; #pragma unroll
;                 for (int bj = 0; bj < 2; ++bj) {
;                     const u32x4 w = raw[m][bj];
;                     const f32x4 r0 = {__uint_as_float(w.x << 16), __uint_as_float(w.x & 0xffff0000u), __uint_as_float(w.y << 16), __uint_as_float(w.y & 0xffff0000u)};
;                     const f32x4 r1 = {__uint_as_float(w.z << 16), __uint_as_float(w.z & 0xffff0000u), __uint_as_float(w.w << 16), __uint_as_float(w.w & 0xffff0000u)};
;                     const f32x4 v0 = r0 + acc[ai][bj][m][0], v1 = r1 + acc[ai][bj][m][1];
;                     if (out32) { *(f32x4*)(out32 + off + bj * HALF) = v0; *(f32x4*)(out32 + off + bj * HALF + 4) = v1; }
;                     if (XB) { u32x4 o; o.x = cvt_pk_bf16(v0[0], v0[1]); o.y = cvt_pk_bf16(v0[2], v0[3]); o.z = cvt_pk_bf16(v1[0], v1[1]); o.w = cvt_pk_bf16(v1[2], v1[3]);
;                               *(u32x4*)(XB + off + bj * HALF) = o;
;                               sq += ((v0[0] * v0[0] + v0[1] * v0[1]) + (v0[2] * v0[2] + v0[3] * v0[3])) + ((v1[0] * v1[0] + v1[1] * v1[1]) + (v1[2] * v1[2] + v1[3] * v1[3])); }
;                 }
;                 if (XB) { sq += __shfl_xor(sq, 16); sq += __shfl_xor(sq, 32); if (fq == 0) SS[(size_t)row * 32 + u.pn * 4 + wc] = sq; }
;             }
.LBB0_801:
	v_lshlrev_b32_e32 v42, 16, v80
	v_and_b32_e32 v43, 0xffff0000, v80
	v_lshlrev_b32_e32 v44, 16, v81
	v_and_b32_e32 v45, 0xffff0000, v81
	v_lshlrev_b32_e32 v46, 16, v82
	v_and_b32_e32 v47, 0xffff0000, v82
	v_lshlrev_b32_e32 v50, 16, v83
	v_and_b32_e32 v51, 0xffff0000, v83
	v_pk_add_f32 v[38:39], v[38:39], v[44:45]
	v_pk_add_f32 v[36:37], v[36:37], v[42:43]
	v_pk_add_f32 v[34:35], v[34:35], v[50:51]
	v_pk_add_f32 v[32:33], v[32:33], v[46:47]
	v_cvt_pk_bf16_f32 v42, v36, v37
	v_cvt_pk_bf16_f32 v43, v38, v39
	v_cvt_pk_bf16_f32 v44, v32, v33
	v_cvt_pk_bf16_f32 v45, v34, v35
	s_and_b64 vcc, exec, s[6:7]
	global_store_dwordx4 v[48:49], v[42:45], off offset:256
	s_cbranch_vccnz .LBB0_805
	v_mul_f32_e32 v33, v33, v33
	v_mul_f32_e32 v37, v37, v37
	v_fmac_f32_e32 v33, v32, v32
	v_mul_f32_e32 v32, v35, v35
	v_fmac_f32_e32 v37, v36, v36
	v_mul_f32_e32 v36, v39, v39
	v_fmac_f32_e32 v32, v34, v34
	v_and_b32_e32 v34, 64, v184
	v_fmac_f32_e32 v36, v38, v38
	v_add_f32_e32 v32, v33, v32
	v_xor_b32_e32 v33, 16, v184
	v_add_u32_e32 v34, 64, v34
	v_add_f32_e32 v36, v37, v36
	v_cmp_lt_i32_e32 vcc, v33, v34
	v_add_f32_e32 v32, v36, v32
	v_add_f32_e32 v32, v32, v40
	v_cndmask_b32_e32 v33, v184, v33, vcc
	v_lshlrev_b32_e32 v33, 2, v33
	ds_bpermute_b32 v33, v33, v32
	s_waitcnt lgkmcnt(0)
	v_add_f32_e32 v32, v32, v33
	v_xor_b32_e32 v33, 32, v184
	v_cmp_lt_i32_e32 vcc, v33, v34
	s_nop 1
	v_cndmask_b32_e32 v33, v184, v33, vcc
	v_lshlrev_b32_e32 v33, 2, v33
	ds_bpermute_b32 v33, v33, v32
	s_and_saveexec_b64 s[28:29], s[2:3]
	s_cbranch_execz .LBB0_804
	v_lshlrev_b64 v[34:35], 7, v[96:97]
	v_lshl_add_u64 v[34:35], s[64:65], 0, v[34:35]
	v_lshl_add_u64 v[34:35], s[26:27], 2, v[34:35]
	s_lshl_b32 s8, s42, 2
	v_lshl_add_u64 v[34:35], v[34:35], 0, s[8:9]
	s_waitcnt lgkmcnt(0)
	v_add_f32_e32 v32, v32, v33
	global_store_dword v[34:35], v32, off

; __device__ __forceinline__ unsigned cvt_pk_bf16(float lo, float hi) { f32x2 v = {lo, hi}; return __builtin_bit_cast(unsigned, __builtin_convertvector(v, bf2_t)); }
;     __device__ __forceinline__ void operator()(const f32x4 (&acc)[2][2][4][2], const Unit& u, int wr, int wc, int fr, int fq) const {
;     ...
;             for (int m = 0; m < 4; ++m) {
;                 const int row = row0 + ai * HALF + m * 16;
;                 const size_t off = (size_t)row * 2048 + col0;
;                 float sq = 0.f;
; #pragma unroll
;                 for (int bj = 0; bj < 2; ++bj) {
;                     const u32x4 w = raw[m][bj];
;                     const f32x4 r0 = {__uint_as_float(w.x << 16), __uint_as_float(w.x & 0xffff0000u), __uint_as_float(w.y << 16), __uint_as_float(w.y & 0xffff0000u)};
;                     const f32x4 r1 = {__uint_as_float(w.z << 16), __uint_as_float(w.z & 0xffff0000u), __uint_as_float(w.w << 16), __uint_as_float(w.w & 0xffff0000u)};
;                     const f32x4 v0 = r0 + acc[ai][bj][m][0], v1 = r1 + acc[ai][bj][m][1];
;                     if (out32) { *(f32x4*)(out32 + off + bj * HALF) = v0; *(f32x4*)(out32 + off + bj * HALF + 4) = v1; }
;                     if (XB) { u32x4 o; o.x = cvt_pk_bf16(v0[0], v0[1]); o.y = cvt_pk_bf16(v0[2], v0[3]); o.z = cvt_pk_bf16(v1[0], v1[1]); o.w = cvt_pk_bf16(v1[2], v1[3]);
;                               *(u32x4*)(XB + off + bj * HALF) = o;
;                               sq += ((v0[0] * v0[0] + v0[1] * v0[1]) + (v0[2] * v0[2] + v0[3] * v0[3])) + ((v1[0] * v1[0] + v1[1] * v1[1]) + (v1[2] * v1[2] + v1[3] * v1[3])); }
;                 }
;                 if (XB) { sq += __shfl_xor(sq, 16); sq += __shfl_xor(sq, 32); if (fq == 0) SS[(size_t)row * 32 + u.pn * 4 + wc] = sq; }
;             }
.LBB0_808:
	v_lshlrev_b32_e32 v26, 16, v72
	v_and_b32_e32 v27, 0xffff0000, v72
	v_lshlrev_b32_e32 v28, 16, v73
	v_and_b32_e32 v29, 0xffff0000, v73
	v_lshlrev_b32_e32 v30, 16, v74
	v_and_b32_e32 v31, 0xffff0000, v74
	v_lshlrev_b32_e32 v34, 16, v75
	v_and_b32_e32 v35, 0xffff0000, v75
	v_pk_add_f32 v[22:23], v[22:23], v[28:29]
	v_pk_add_f32 v[20:21], v[20:21], v[26:27]
	v_pk_add_f32 v[18:19], v[18:19], v[34:35]
	v_pk_add_f32 v[16:17], v[16:17], v[30:31]
	v_cvt_pk_bf16_f32 v26, v20, v21
	v_cvt_pk_bf16_f32 v27, v22, v23
	v_cvt_pk_bf16_f32 v28, v16, v17
	v_cvt_pk_bf16_f32 v29, v18, v19
	s_and_b64 vcc, exec, s[6:7]
	global_store_dwordx4 v[32:33], v[26:29], off offset:256
	s_cbranch_vccnz .LBB0_812
	v_mul_f32_e32 v17, v17, v17
	v_mul_f32_e32 v21, v21, v21
	v_fmac_f32_e32 v17, v16, v16
	v_mul_f32_e32 v16, v19, v19
	v_fmac_f32_e32 v21, v20, v20
	v_mul_f32_e32 v20, v23, v23
	v_fmac_f32_e32 v16, v18, v18
	v_and_b32_e32 v18, 64, v184
	v_fmac_f32_e32 v20, v22, v22
	v_add_f32_e32 v16, v17, v16
	v_xor_b32_e32 v17, 16, v184
	v_add_u32_e32 v18, 64, v18
	v_add_f32_e32 v20, v21, v20
	v_cmp_lt_i32_e32 vcc, v17, v18
	v_add_f32_e32 v16, v20, v16
	v_add_f32_e32 v16, v16, v24
	v_cndmask_b32_e32 v17, v184, v17, vcc
	v_lshlrev_b32_e32 v17, 2, v17
	ds_bpermute_b32 v17, v17, v16
	s_waitcnt lgkmcnt(0)
	v_add_f32_e32 v16, v16, v17
	v_xor_b32_e32 v17, 32, v184
	v_cmp_lt_i32_e32 vcc, v17, v18
	s_nop 1
	v_cndmask_b32_e32 v17, v184, v17, vcc
	v_lshlrev_b32_e32 v17, 2, v17
	ds_bpermute_b32 v17, v17, v16
	s_and_saveexec_b64 s[28:29], s[2:3]
	s_cbranch_execz .LBB0_811
	v_lshlrev_b64 v[18:19], 7, v[94:95]
	v_lshl_add_u64 v[18:19], s[64:65], 0, v[18:19]
	v_lshl_add_u64 v[18:19], s[26:27], 2, v[18:19]
	s_lshl_b32 s8, s42, 2
	v_lshl_add_u64 v[18:19], v[18:19], 0, s[8:9]
	s_waitcnt lgkmcnt(0)
	v_add_f32_e32 v16, v16, v17
	global_store_dword v[18:19], v16, off

; __device__ __forceinline__ unsigned cvt_pk_bf16(float lo, float hi) { f32x2 v = {lo, hi}; return __builtin_bit_cast(unsigned, __builtin_convertvector(v, bf2_t)); }
;     __device__ __forceinline__ void operator()(const f32x4 (&acc)[2][2][4][2], const Unit& u, int wr, int wc, int fr, int fq) const {
;     ...
;             for (int m = 0; m < 4; ++m) {
;                 const int row = row0 + ai * HALF + m * 16;
;                 const size_t off = (size_t)row * 2048 + col0;
;                 float sq = 0.f;
; #pragma unroll
;                 for (int bj = 0; bj < 2; ++bj) {
;                     const u32x4 w = raw[m][bj];
;                     const f32x4 r0 = {__uint_as_float(w.x << 16), __uint_as_float(w.x & 0xffff0000u), __uint_as_float(w.y << 16), __uint_as_float(w.y & 0xffff0000u)};
;                     const f32x4 r1 = {__uint_as_float(w.z << 16), __uint_as_float(w.z & 0xffff0000u), __uint_as_float(w.w << 16), __uint_as_float(w.w & 0xffff0000u)};
;                     const f32x4 v0 = r0 + acc[ai][bj][m][0], v1 = r1 + acc[ai][bj][m][1];
;                     if (out32) { *(f32x4*)(out32 + off + bj * HALF) = v0; *(f32x4*)(out32 + off + bj * HALF + 4) = v1; }
;                     if (XB) { u32x4 o; o.x = cvt_pk_bf16(v0[0], v0[1]); o.y = cvt_pk_bf16(v0[2], v0[3]); o.z = cvt_pk_bf16(v1[0], v1[1]); o.w = cvt_pk_bf16(v1[2], v1[3]);
;                               *(u32x4*)(XB + off + bj * HALF) = o;
;                               sq += ((v0[0] * v0[0] + v0[1] * v0[1]) + (v0[2] * v0[2] + v0[3] * v0[3])) + ((v1[0] * v1[0] + v1[1] * v1[1]) + (v1[2] * v1[2] + v1[3] * v1[3])); }
;                 }
;                 if (XB) { sq += __shfl_xor(sq, 16); sq += __shfl_xor(sq, 32); if (fq == 0) SS[(size_t)row * 32 + u.pn * 4 + wc] = sq; }
;             }
.LBB0_815:
	v_lshlrev_b32_e32 v10, 16, v64
	v_and_b32_e32 v11, 0xffff0000, v64
	v_lshlrev_b32_e32 v12, 16, v65
	v_and_b32_e32 v13, 0xffff0000, v65
	v_lshlrev_b32_e32 v14, 16, v66
	v_and_b32_e32 v15, 0xffff0000, v66
	v_pk_add_f32 v[6:7], v[6:7], v[12:13]
	v_pk_add_f32 v[4:5], v[4:5], v[10:11]
	v_lshlrev_b32_e32 v18, 16, v67
	v_and_b32_e32 v19, 0xffff0000, v67
	v_pk_add_f32 v[12:13], v[0:1], v[14:15]
	v_mul_f32_e32 v0, v5, v5
	v_mul_f32_e32 v1, v7, v7
	v_pk_add_f32 v[10:11], v[2:3], v[18:19]
	v_fmac_f32_e32 v0, v4, v4
	v_fmac_f32_e32 v1, v6, v6
	v_add_f32_e32 v0, v0, v1
	v_mul_f32_e32 v1, v13, v13
	v_mul_f32_e32 v2, v11, v11
	v_fmac_f32_e32 v1, v12, v12
	v_fmac_f32_e32 v2, v10, v10
	v_add_f32_e32 v1, v1, v2
	v_and_b32_e32 v2, 64, v184
	v_add_f32_e32 v0, v0, v1
	v_xor_b32_e32 v1, 16, v184
	v_add_u32_e32 v3, 64, v2
	v_cmp_lt_i32_e32 vcc, v1, v3
	v_add_f32_e32 v0, v0, v8
	v_cvt_pk_bf16_f32 v2, v4, v5
	v_cndmask_b32_e32 v1, v184, v1, vcc
	v_lshlrev_b32_e32 v1, 2, v1
	ds_bpermute_b32 v1, v1, v0
	v_cvt_pk_bf16_f32 v4, v12, v13
	v_cvt_pk_bf16_f32 v5, v10, v11
	s_waitcnt lgkmcnt(0)
	v_add_f32_e32 v0, v0, v1
	v_xor_b32_e32 v1, 32, v184
	v_cmp_lt_i32_e32 vcc, v1, v3
	v_cvt_pk_bf16_f32 v3, v6, v7
	global_store_dwordx4 v[16:17], v[2:5], off offset:256
	v_cndmask_b32_e32 v1, v184, v1, vcc
	v_lshlrev_b32_e32 v1, 2, v1
	ds_bpermute_b32 v1, v1, v0
	s_and_saveexec_b64 s[6:7], s[2:3]
	s_cbranch_execz .LBB0_817
	v_lshlrev_b64 v[2:3], 7, v[92:93]
	v_lshl_add_u64 v[2:3], s[64:65], 0, v[2:3]
	v_lshl_add_u64 v[2:3], s[26:27], 2, v[2:3]
	s_lshl_b32 s8, s42, 2
	v_lshl_add_u64 v[2:3], v[2:3], 0, s[8:9]
	s_waitcnt lgkmcnt(0)
	v_add_f32_e32 v0, v0, v1
	global_store_dword v[2:3], v0, off

;     __device__ bool next(int i, pg8::Unit& u) const { const int cnt = (nwg - c + G - 1) / G; if (i >= reps * cnt) return false; return pg8::StaticOrder::next(i % cnt, u); }
; template <class Epi, class Sched, bool ALIGN_EPI = false, bool SP2 = false>
; __device__ __forceinline__ void gemm_phase(PG8_LAS unsigned char* lds, const Gemm g, const Sched& S, const Epi& E) {
;     ...
;         const bool has_next = S.next(ui + 1, nxt);
;         const char* nA = has_next ? (const char*)g.A + (size_t)nxt.pm * tstep : cA; const char* nB = has_next ? (const char*)g.Bt + (size_t)nxt.pn * tstep : cB;
;         for (int t = 0; t < nt; t += 2) {
;             const bool last = (t == nt - 2);
;             const char* a1 = cA + (size_t)(t + 1) * kstep;
;             const char* a2 = last ? nA : cA + (size_t)(t + 2) * kstep; const char* b2 = last ? nB : cB + (size_t)(t + 2) * kstep;
;     ...
; #pragma unroll
;         for (int a = 0; a < 2; ++a)
; #pragma unroll
;             for (int b = 0; b < 2; ++b)
; #pragma unroll
;                 for (int m = 0; m < 4; ++m)
; #pragma unroll
;                     for (int n = 0; n < 2; ++n) acc[a][b][m][n] = (f32x4){0.f, 0.f, 0.f, 0.f};
.LBB0_954:
	s_ashr_i32 s53, s52, 31
	s_lshl_b64 s[22:23], s[52:53], 20
	s_add_u32 s54, s74, s22
	s_addc_u32 s55, s75, s23
	s_and_b64 s[24:25], s[62:63], exec
	s_cselect_b32 s1, s55, s27
	s_cselect_b32 s5, s54, s26
	s_ashr_i32 s41, s40, 31
	s_lshl_b64 s[24:25], s[40:41], 20
	s_add_u32 s56, s94, s24
	s_addc_u32 s57, s95, s25
	s_and_b64 s[30:31], s[62:63], exec
	s_cselect_b32 s17, s57, s29
	s_cselect_b32 s19, s56, s28
	s_add_u32 s26, s26, 0x80080
	s_addc_u32 s27, s27, 0
	s_add_u32 s33, s28, 0x100
	v_mov_b64_e32 v[0:1], 0
	v_mov_b64_e32 v[2:3], 0
	v_mov_b64_e32 v[4:5], 0
	v_mov_b64_e32 v[6:7], 0
	v_mov_b64_e32 v[8:9], 0
	v_mov_b64_e32 v[10:11], 0
	v_mov_b64_e32 v[12:13], 0
	v_mov_b64_e32 v[14:15], 0
	v_mov_b64_e32 v[16:17], 0
	v_mov_b64_e32 v[18:19], 0
	v_mov_b64_e32 v[20:21], 0
	v_mov_b64_e32 v[22:23], 0
	v_mov_b64_e32 v[24:25], 0
	v_mov_b64_e32 v[26:27], 0
	v_mov_b64_e32 v[28:29], 0
	v_mov_b64_e32 v[30:31], 0
	v_mov_b64_e32 v[32:33], 0
	v_mov_b64_e32 v[34:35], 0
	v_mov_b64_e32 v[36:37], 0
	v_mov_b64_e32 v[38:39], 0
	v_mov_b64_e32 v[40:41], 0
	v_mov_b64_e32 v[42:43], 0
	v_mov_b64_e32 v[44:45], 0
	v_mov_b64_e32 v[46:47], 0
	v_mov_b64_e32 v[48:49], 0
	v_mov_b64_e32 v[50:51], 0
	v_mov_b64_e32 v[52:53], 0
	v_mov_b64_e32 v[54:55], 0
	v_mov_b64_e32 v[56:57], 0
	v_mov_b64_e32 v[58:59], 0
	v_mov_b64_e32 v[60:61], 0
	v_mov_b64_e32 v[62:63], 0
	v_mov_b64_e32 v[64:65], 0
	v_mov_b64_e32 v[66:67], 0
	v_mov_b64_e32 v[68:69], 0
	v_mov_b64_e32 v[70:71], 0
	v_mov_b64_e32 v[72:73], 0
	v_mov_b64_e32 v[74:75], 0
	v_mov_b64_e32 v[76:77], 0
	v_mov_b64_e32 v[78:79], 0
	v_mov_b64_e32 v[80:81], 0
	v_mov_b64_e32 v[82:83], 0
	v_mov_b64_e32 v[84:85], 0
	v_mov_b64_e32 v[86:87], 0
	v_mov_b64_e32 v[88:89], 0
	v_mov_b64_e32 v[90:91], 0
	v_mov_b64_e32 v[92:93], 0
	v_mov_b64_e32 v[94:95], 0
	v_mov_b64_e32 v[96:97], 0
	v_mov_b64_e32 v[98:99], 0
	v_mov_b64_e32 v[100:101], 0
	v_mov_b64_e32 v[102:103], 0
	v_mov_b64_e32 v[104:105], 0
	v_mov_b64_e32 v[106:107], 0
	v_mov_b64_e32 v[108:109], 0
	v_mov_b64_e32 v[110:111], 0
	v_mov_b64_e32 v[112:113], 0
	v_mov_b64_e32 v[114:115], 0
	v_mov_b64_e32 v[116:117], 0
	v_mov_b64_e32 v[118:119], 0
	v_mov_b64_e32 v[120:121], 0
	v_mov_b64_e32 v[122:123], 0
	v_mov_b64_e32 v[124:125], 0
	v_mov_b64_e32 v[126:127], 0
	s_addc_u32 s44, s29, 0
	s_mov_b32 s45, -2
	s_waitcnt vmcnt(0)

;     __device__ bool next(int i, pg8::Unit& u) const { const int cnt = (nwg - c + G - 1) / G; if (i >= reps * cnt) return false; return pg8::StaticOrder::next(i % cnt, u); }
; template <class Epi, class Sched, bool ALIGN_EPI = false, bool SP2 = false>
; __device__ __forceinline__ void gemm_phase(PG8_LAS unsigned char* lds, const Gemm g, const Sched& S, const Epi& E) {
;     ...
;         const bool has_next = S.next(ui + 1, nxt);
;         const char* nA = has_next ? (const char*)g.A + (size_t)nxt.pm * tstep : cA; const char* nB = has_next ? (const char*)g.Bt + (size_t)nxt.pn * tstep : cB;
;         for (int t = 0; t < nt; t += 2) {
;             const bool last = (t == nt - 2);
;             const char* a1 = cA + (size_t)(t + 1) * kstep;
;             const char* a2 = last ? nA : cA + (size_t)(t + 2) * kstep; const char* b2 = last ? nB : cB + (size_t)(t + 2) * kstep;
;     ...
; #pragma unroll
;         for (int a = 0; a < 2; ++a)
; #pragma unroll
;             for (int b = 0; b < 2; ++b)
; #pragma unroll
;                 for (int m = 0; m < 4; ++m)
; #pragma unroll
;                     for (int n = 0; n < 2; ++n) acc[a][b][m][n] = (f32x4){0.f, 0.f, 0.f, 0.f};
.LBB0_1179:
	s_ashr_i32 s21, s20, 31
	s_lshl_b64 s[22:23], s[20:21], 20
	s_add_u32 s22, s56, s22
	s_addc_u32 s23, s57, s23
	s_and_b64 s[24:25], s[4:5], exec
	s_cselect_b32 s7, s23, s27
	s_cselect_b32 s21, s22, s26
	s_ashr_i32 s19, s18, 31
	s_lshl_b64 s[24:25], s[18:19], 20
	s_add_u32 s24, s68, s24
	s_addc_u32 s25, s69, s25
	s_and_b64 s[30:31], s[4:5], exec
	s_cselect_b32 s19, s25, s29
	s_cselect_b32 s46, s24, s28
	s_add_u32 s26, s26, 0x80080
	s_addc_u32 s27, s27, 0
	s_add_u32 s47, s28, 0x100
	v_mov_b64_e32 v[0:1], 0
	v_mov_b64_e32 v[2:3], 0
	v_mov_b64_e32 v[4:5], 0
	v_mov_b64_e32 v[6:7], 0
	v_mov_b64_e32 v[8:9], 0
	v_mov_b64_e32 v[10:11], 0
	v_mov_b64_e32 v[12:13], 0
	v_mov_b64_e32 v[14:15], 0
	v_mov_b64_e32 v[16:17], 0
	v_mov_b64_e32 v[18:19], 0
	v_mov_b64_e32 v[20:21], 0
	v_mov_b64_e32 v[22:23], 0
	v_mov_b64_e32 v[24:25], 0
	v_mov_b64_e32 v[26:27], 0
	v_mov_b64_e32 v[28:29], 0
	v_mov_b64_e32 v[30:31], 0
	v_mov_b64_e32 v[32:33], 0
	v_mov_b64_e32 v[34:35], 0
	v_mov_b64_e32 v[36:37], 0
	v_mov_b64_e32 v[38:39], 0
	v_mov_b64_e32 v[40:41], 0
	v_mov_b64_e32 v[42:43], 0
	v_mov_b64_e32 v[44:45], 0
	v_mov_b64_e32 v[46:47], 0
	v_mov_b64_e32 v[48:49], 0
	v_mov_b64_e32 v[50:51], 0
	v_mov_b64_e32 v[52:53], 0
	v_mov_b64_e32 v[54:55], 0
	v_mov_b64_e32 v[56:57], 0
	v_mov_b64_e32 v[58:59], 0
	v_mov_b64_e32 v[60:61], 0
	v_mov_b64_e32 v[62:63], 0
	v_mov_b64_e32 v[64:65], 0
	v_mov_b64_e32 v[66:67], 0
	v_mov_b64_e32 v[68:69], 0
	v_mov_b64_e32 v[70:71], 0
	v_mov_b64_e32 v[72:73], 0
	v_mov_b64_e32 v[74:75], 0
	v_mov_b64_e32 v[76:77], 0
	v_mov_b64_e32 v[78:79], 0
	v_mov_b64_e32 v[80:81], 0
	v_mov_b64_e32 v[82:83], 0
	v_mov_b64_e32 v[84:85], 0
	v_mov_b64_e32 v[86:87], 0
	v_mov_b64_e32 v[88:89], 0
	v_mov_b64_e32 v[90:91], 0
	v_mov_b64_e32 v[92:93], 0
	v_mov_b64_e32 v[94:95], 0
	v_mov_b64_e32 v[96:97], 0
	v_mov_b64_e32 v[98:99], 0
	v_mov_b64_e32 v[100:101], 0
	v_mov_b64_e32 v[102:103], 0
	v_mov_b64_e32 v[104:105], 0
	v_mov_b64_e32 v[106:107], 0
	v_mov_b64_e32 v[108:109], 0
	v_mov_b64_e32 v[110:111], 0
	v_mov_b64_e32 v[112:113], 0
	v_mov_b64_e32 v[114:115], 0
	v_mov_b64_e32 v[116:117], 0
	v_mov_b64_e32 v[118:119], 0
	v_mov_b64_e32 v[120:121], 0
	v_mov_b64_e32 v[122:123], 0
	v_mov_b64_e32 v[124:125], 0
	v_mov_b64_e32 v[126:127], 0
	s_addc_u32 s48, s29, 0
	s_mov_b32 s49, -2
	s_waitcnt lgkmcnt(0)

; __device__ __forceinline__ unsigned cvt_pk_bf16(float lo, float hi) { f32x2 v = {lo, hi}; return __builtin_bit_cast(unsigned, __builtin_convertvector(v, bf2_t)); }
;     __device__ __forceinline__ void operator()(const f32x4 (&acc)[2][2][4][2], const Unit& u, int wr, int wc, int fr, int fq) const {
;         const int row0 = u.pm * BM + wr * 64 + fr, col0 = u.pn * BM + wc * 32 + 8 * fq;
; #pragma unroll
;         for (int ai = 0; ai < 2; ++ai) {
;             u32x4 raw[4][2];
; #pragma unroll
;             for (int m = 0; m < 4; ++m)
; #pragma unroll
;                 for (int bj = 0; bj < 2; ++bj) raw[m][bj] = *(const u32x4*)(base16 + (size_t)(row0 + ai * HALF + m * 16) * 2048 + col0 + bj * HALF);
; #pragma unroll
;             for (int m = 0; m < 4; ++m) {
;                 const int row = row0 + ai * HALF + m * 16;
;                 const size_t off = (size_t)row * 2048 + col0;
;                 float sq = 0.f;
; #pragma unroll
;                 for (int bj = 0; bj < 2; ++bj) {
;                     const u32x4 w = raw[m][bj];
;                     const f32x4 r0 = {__uint_as_float(w.x << 16), __uint_as_float(w.x & 0xffff0000u), __uint_as_float(w.y << 16), __uint_as_float(w.y & 0xffff0000u)};
;                     const f32x4 r1 = {__uint_as_float(w.z << 16), __uint_as_float(w.z & 0xffff0000u), __uint_as_float(w.w << 16), __uint_as_float(w.w & 0xffff0000u)};
;                     const f32x4 v0 = r0 + acc[ai][bj][m][0], v1 = r1 + acc[ai][bj][m][1];
;                     if (out32) { *(f32x4*)(out32 + off + bj * HALF) = v0; *(f32x4*)(out32 + off + bj * HALF + 4) = v1; }
;                     if (XB) { u32x4 o; o.x = cvt_pk_bf16(v0[0], v0[1]); o.y = cvt_pk_bf16(v0[2], v0[3]); o.z = cvt_pk_bf16(v1[0], v1[1]); o.w = cvt_pk_bf16(v1[2], v1[3]);
;                               *(u32x4*)(XB + off + bj * HALF) = o;
;                               sq += ((v0[0] * v0[0] + v0[1] * v0[1]) + (v0[2] * v0[2] + v0[3] * v0[3])) + ((v1[0] * v1[0] + v1[1] * v1[1]) + (v1[2] * v1[2] + v1[3] * v1[3])); }
;                 }
;                 if (XB) { sq += __shfl_xor(sq, 16); sq += __shfl_xor(sq, 32); if (fq == 0) SS[(size_t)row * 32 + u.pn * 4 + wc] = sq; }
;             }
.LBB0_1183:
	v_lshl_or_b32 v128, s6, 8, v180
	v_lshl_add_u32 v170, s8, 8, v178
	v_ashrrev_i32_e32 v129, 31, v128
	v_lshlrev_b64 v[194:195], 1, v[128:129]
	v_ashrrev_i32_e32 v171, 31, v170
	v_lshl_add_u64 v[168:169], s[74:75], 0, v[194:195]
	v_lshlrev_b64 v[198:199], 12, v[170:171]
	v_or_b32_e32 v176, 16, v170
	v_or_b32_e32 v174, 32, v170
	v_lshl_add_u64 v[128:129], v[168:169], 0, v[198:199]
	v_or_b32_e32 v172, 48, v170
	v_ashrrev_i32_e32 v177, 31, v176
	v_ashrrev_i32_e32 v175, 31, v174
	global_load_dwordx4 v[186:189], v[128:129], off
	global_load_dwordx4 v[190:193], v[128:129], off offset:256
	v_ashrrev_i32_e32 v173, 31, v172
	v_lshlrev_b64 v[128:129], 12, v[176:177]
	v_lshlrev_b64 v[130:131], 12, v[174:175]
	v_lshlrev_b64 v[132:133], 12, v[172:173]
	v_lshl_add_u64 v[128:129], v[168:169], 0, v[128:129]
	v_lshl_add_u64 v[130:131], v[168:169], 0, v[130:131]
	v_lshl_add_u64 v[200:201], v[168:169], 0, v[132:133]
	global_load_dwordx4 v[148:151], v[128:129], off
	global_load_dwordx4 v[144:147], v[128:129], off offset:256
	global_load_dwordx4 v[140:143], v[130:131], off
	global_load_dwordx4 v[136:139], v[130:131], off offset:256
	global_load_dwordx4 v[132:135], v[200:201], off
	s_nop 0
	global_load_dwordx4 v[128:131], v[200:201], off offset:256
	v_lshl_add_u64 v[198:199], s[74:75], 0, v[198:199]
	v_lshl_add_u64 v[194:195], v[198:199], 0, v[194:195]
	s_lshl_b32 s26, s6, 2
	v_cndmask_b32_e64 v185, 0, 1, s[16:17]
	s_ashr_i32 s27, s26, 31
	v_cmp_ne_u32_e64 s[6:7], 1, v185
	s_andn2_b64 vcc, exec, s[16:17]
	v_add_u32_e32 v244, 0x80, v170
	v_ashrrev_i32_e32 v245, 31, v244
	v_lshlrev_b64 v[244:245], 12, v[244:245]
	v_lshl_add_u64 v[244:245], v[168:169], 0, v[244:245]
	global_load_dwordx4 v[206:209], v[244:245], off
	global_load_dwordx4 v[210:213], v[244:245], off offset:256
	v_add_u32_e32 v244, 0x90, v170
	v_ashrrev_i32_e32 v245, 31, v244
	v_lshlrev_b64 v[244:245], 12, v[244:245]
	v_lshl_add_u64 v[244:245], v[168:169], 0, v[244:245]
	global_load_dwordx4 v[214:217], v[244:245], off
	global_load_dwordx4 v[218:221], v[244:245], off offset:256
	v_add_u32_e32 v244, 0xa0, v170
	v_ashrrev_i32_e32 v245, 31, v244
	v_lshlrev_b64 v[244:245], 12, v[244:245]
	v_lshl_add_u64 v[244:245], v[168:169], 0, v[244:245]
	global_load_dwordx4 v[228:231], v[244:245], off
	global_load_dwordx4 v[232:235], v[244:245], off offset:256
	v_add_u32_e32 v244, 0xb0, v170
	v_ashrrev_i32_e32 v245, 31, v244
	v_lshlrev_b64 v[244:245], 12, v[244:245]
	v_lshl_add_u64 v[244:245], v[168:169], 0, v[244:245]
	global_load_dwordx4 v[236:239], v[244:245], off
	global_load_dwordx4 v[240:243], v[244:245], off offset:256
	s_waitcnt vmcnt(0)
	v_lshlrev_b32_e32 v198, 16, v186
	v_and_b32_e32 v199, 0xffff0000, v186
	v_lshlrev_b32_e32 v186, 16, v187
	v_and_b32_e32 v187, 0xffff0000, v187
	v_lshlrev_b32_e32 v200, 16, v188
	v_and_b32_e32 v201, 0xffff0000, v188
	v_lshlrev_b32_e32 v188, 16, v189
	v_and_b32_e32 v189, 0xffff0000, v189
	v_lshlrev_b32_e32 v202, 16, v190
	v_and_b32_e32 v203, 0xffff0000, v190
	v_lshlrev_b32_e32 v190, 16, v191
	v_and_b32_e32 v191, 0xffff0000, v191
	v_lshlrev_b32_e32 v204, 16, v192
	v_and_b32_e32 v205, 0xffff0000, v192
	v_lshlrev_b32_e32 v192, 16, v193
	v_and_b32_e32 v193, 0xffff0000, v193
	v_pk_add_f32 v[126:127], v[126:127], v[186:187]
	v_pk_add_f32 v[124:125], v[124:125], v[198:199]
	v_pk_add_f32 v[122:123], v[122:123], v[188:189]
	v_pk_add_f32 v[120:121], v[120:121], v[200:201]
	v_pk_add_f32 v[118:119], v[118:119], v[190:191]
	v_pk_add_f32 v[116:117], v[116:117], v[202:203]
	v_pk_add_f32 v[114:115], v[114:115], v[192:193]
	v_pk_add_f32 v[112:113], v[112:113], v[204:205]
	v_cvt_pk_bf16_f32 v186, v124, v125
	v_cvt_pk_bf16_f32 v187, v126, v127
	v_cvt_pk_bf16_f32 v188, v120, v121
	v_cvt_pk_bf16_f32 v189, v122, v123
	v_cvt_pk_bf16_f32 v190, v116, v117
	v_cvt_pk_bf16_f32 v191, v118, v119
	v_cvt_pk_bf16_f32 v192, v112, v113
	v_cvt_pk_bf16_f32 v193, v114, v115
	global_store_dwordx4 v[194:195], v[186:189], off
	global_store_dwordx4 v[194:195], v[190:193], off offset:256
	s_cbranch_vccnz .LBB0_1187
	v_mul_f32_e32 v113, v113, v113
	v_mul_f32_e32 v125, v125, v125
	v_mul_f32_e32 v121, v121, v121
	v_mul_f32_e32 v117, v117, v117
	v_fmac_f32_e32 v113, v112, v112
	v_mul_f32_e32 v112, v115, v115
	v_fmac_f32_e32 v125, v124, v124
	v_mul_f32_e32 v124, v127, v127
	v_fmac_f32_e32 v121, v120, v120
	v_mul_f32_e32 v120, v123, v123
	v_fmac_f32_e32 v117, v116, v116
	v_mul_f32_e32 v116, v119, v119
	v_fmac_f32_e32 v112, v114, v114
	v_and_b32_e32 v114, 64, v184
	v_fmac_f32_e32 v124, v126, v126
	v_fmac_f32_e32 v120, v122, v122
	v_fmac_f32_e32 v116, v118, v118
	v_add_f32_e32 v112, v113, v112
	v_xor_b32_e32 v113, 16, v184
	v_add_u32_e32 v114, 64, v114
	v_add_f32_e32 v124, v125, v124
	v_add_f32_e32 v120, v121, v120
	v_add_f32_e32 v116, v117, v116
	v_cmp_lt_i32_e32 vcc, v113, v114
	v_add_f32_e32 v120, v124, v120
	v_add_f32_e32 v112, v116, v112
	v_cndmask_b32_e32 v113, v184, v113, vcc
	v_add_f32_e32 v112, v120, v112
	v_lshlrev_b32_e32 v113, 2, v113
	ds_bpermute_b32 v113, v113, v112
	s_waitcnt lgkmcnt(0)
	v_add_f32_e32 v112, v112, v113
	v_xor_b32_e32 v113, 32, v184
	v_cmp_lt_i32_e32 vcc, v113, v114
	s_nop 1
	v_cndmask_b32_e32 v113, v184, v113, vcc
	v_lshlrev_b32_e32 v113, 2, v113
	ds_bpermute_b32 v113, v113, v112
	s_and_saveexec_b64 s[28:29], s[2:3]
	s_cbranch_execz .LBB0_1186
	v_lshlrev_b64 v[114:115], 7, v[170:171]
	v_lshl_add_u64 v[114:115], s[64:65], 0, v[114:115]
	v_lshl_add_u64 v[114:115], s[26:27], 2, v[114:115]
	s_lshl_b32 s8, s38, 2
	v_lshl_add_u64 v[114:115], v[114:115], 0, s[8:9]
	s_waitcnt lgkmcnt(0)
	v_add_f32_e32 v112, v112, v113
	global_store_dword v[114:115], v112, off

; __device__ __forceinline__ unsigned cvt_pk_bf16(float lo, float hi) { f32x2 v = {lo, hi}; return __builtin_bit_cast(unsigned, __builtin_convertvector(v, bf2_t)); }
;     __device__ __forceinline__ void operator()(const f32x4 (&acc)[2][2][4][2], const Unit& u, int wr, int wc, int fr, int fq) const {
;     ...
;             for (int m = 0; m < 4; ++m) {
;                 const int row = row0 + ai * HALF + m * 16;
;                 const size_t off = (size_t)row * 2048 + col0;
;                 float sq = 0.f;
; #pragma unroll
;                 for (int bj = 0; bj < 2; ++bj) {
;                     const u32x4 w = raw[m][bj];
;                     const f32x4 r0 = {__uint_as_float(w.x << 16), __uint_as_float(w.x & 0xffff0000u), __uint_as_float(w.y << 16), __uint_as_float(w.y & 0xffff0000u)};
;                     const f32x4 r1 = {__uint_as_float(w.z << 16), __uint_as_float(w.z & 0xffff0000u), __uint_as_float(w.w << 16), __uint_as_float(w.w & 0xffff0000u)};
;                     const f32x4 v0 = r0 + acc[ai][bj][m][0], v1 = r1 + acc[ai][bj][m][1];
;                     if (out32) { *(f32x4*)(out32 + off + bj * HALF) = v0; *(f32x4*)(out32 + off + bj * HALF + 4) = v1; }
;                     if (XB) { u32x4 o; o.x = cvt_pk_bf16(v0[0], v0[1]); o.y = cvt_pk_bf16(v0[2], v0[3]); o.z = cvt_pk_bf16(v1[0], v1[1]); o.w = cvt_pk_bf16(v1[2], v1[3]);
;                               *(u32x4*)(XB + off + bj * HALF) = o;
;                               sq += ((v0[0] * v0[0] + v0[1] * v0[1]) + (v0[2] * v0[2] + v0[3] * v0[3])) + ((v1[0] * v1[0] + v1[1] * v1[1]) + (v1[2] * v1[2] + v1[3] * v1[3])); }
;                 }
;                 if (XB) { sq += __shfl_xor(sq, 16); sq += __shfl_xor(sq, 32); if (fq == 0) SS[(size_t)row * 32 + u.pn * 4 + wc] = sq; }
;             }
.LBB0_1211:
	v_lshlrev_b32_e32 v58, 16, v88
	v_and_b32_e32 v59, 0xffff0000, v88
	v_lshlrev_b32_e32 v60, 16, v89
	v_and_b32_e32 v61, 0xffff0000, v89
	v_lshlrev_b32_e32 v62, 16, v90
	v_and_b32_e32 v63, 0xffff0000, v90
	v_lshlrev_b32_e32 v88, 16, v91
	v_and_b32_e32 v89, 0xffff0000, v91
	v_pk_add_f32 v[54:55], v[54:55], v[60:61]
	v_pk_add_f32 v[52:53], v[52:53], v[58:59]
	v_pk_add_f32 v[50:51], v[50:51], v[88:89]
	v_pk_add_f32 v[48:49], v[48:49], v[62:63]
	v_cvt_pk_bf16_f32 v58, v52, v53
	v_cvt_pk_bf16_f32 v59, v54, v55
	v_cvt_pk_bf16_f32 v60, v48, v49
	v_cvt_pk_bf16_f32 v61, v50, v51
	s_and_b64 vcc, exec, s[6:7]
	global_store_dwordx4 v[100:101], v[58:61], off offset:256
	s_cbranch_vccnz .LBB0_1215
	v_mul_f32_e32 v49, v49, v49
	v_mul_f32_e32 v53, v53, v53
	v_fmac_f32_e32 v49, v48, v48
	v_mul_f32_e32 v48, v51, v51
	v_fmac_f32_e32 v53, v52, v52
	v_mul_f32_e32 v52, v55, v55
	v_fmac_f32_e32 v48, v50, v50
	v_and_b32_e32 v50, 64, v184
	v_fmac_f32_e32 v52, v54, v54
	v_add_f32_e32 v48, v49, v48
	v_xor_b32_e32 v49, 16, v184
	v_add_u32_e32 v50, 64, v50
	v_add_f32_e32 v52, v53, v52
	v_cmp_lt_i32_e32 vcc, v49, v50
	v_add_f32_e32 v48, v52, v48
	v_add_f32_e32 v48, v48, v56
	v_cndmask_b32_e32 v49, v184, v49, vcc
	v_lshlrev_b32_e32 v49, 2, v49
	ds_bpermute_b32 v49, v49, v48
	s_waitcnt lgkmcnt(0)
	v_add_f32_e32 v48, v48, v49
	v_xor_b32_e32 v49, 32, v184
	v_cmp_lt_i32_e32 vcc, v49, v50
	s_nop 1
	v_cndmask_b32_e32 v49, v184, v49, vcc
	v_lshlrev_b32_e32 v49, 2, v49
	ds_bpermute_b32 v49, v49, v48
	s_and_saveexec_b64 s[28:29], s[2:3]
	s_cbranch_execz .LBB0_1214
	v_lshlrev_b64 v[50:51], 7, v[98:99]
	v_lshl_add_u64 v[50:51], s[64:65], 0, v[50:51]
	v_lshl_add_u64 v[50:51], s[26:27], 2, v[50:51]
	s_lshl_b32 s8, s38, 2
	v_lshl_add_u64 v[50:51], v[50:51], 0, s[8:9]
	s_waitcnt lgkmcnt(0)
	v_add_f32_e32 v48, v48, v49
	global_store_dword v[50:51], v48, off

; __device__ __forceinline__ unsigned cvt_pk_bf16(float lo, float hi) { f32x2 v = {lo, hi}; return __builtin_bit_cast(unsigned, __builtin_convertvector(v, bf2_t)); }
;     __device__ __forceinline__ void operator()(const f32x4 (&acc)[2][2][4][2], const Unit& u, int wr, int wc, int fr, int fq) const {
;     ...
;             for (int m = 0; m < 4; ++m) {
;                 const int row = row0 + ai * HALF + m * 16;
;                 const size_t off = (size_t)row * 2048 + col0;
;                 float sq = 0.f;
; #pragma unroll
;                 for (int bj = 0; bj < 2; ++bj) {
;                     const u32x4 w = raw[m][bj];
;                     const f32x4 r0 = {__uint_as_float(w.x << 16), __uint_as_float(w.x & 0xffff0000u), __uint_as_float(w.y << 16), __uint_as_float(w.y & 0xffff0000u)};
;                     const f32x4 r1 = {__uint_as_float(w.z << 16), __uint_as_float(w.z & 0xffff0000u), __uint_as_float(w.w << 16), __uint_as_float(w.w & 0xffff0000u)};
;                     const f32x4 v0 = r0 + acc[ai][bj][m][0], v1 = r1 + acc[ai][bj][m][1];
;                     if (out32) { *(f32x4*)(out32 + off + bj * HALF) = v0; *(f32x4*)(out32 + off + bj * HALF + 4) = v1; }
;                     if (XB) { u32x4 o; o.x = cvt_pk_bf16(v0[0], v0[1]); o.y = cvt_pk_bf16(v0[2], v0[3]); o.z = cvt_pk_bf16(v1[0], v1[1]); o.w = cvt_pk_bf16(v1[2], v1[3]);
;                               *(u32x4*)(XB + off + bj * HALF) = o;
;                               sq += ((v0[0] * v0[0] + v0[1] * v0[1]) + (v0[2] * v0[2] + v0[3] * v0[3])) + ((v1[0] * v1[0] + v1[1] * v1[1]) + (v1[2] * v1[2] + v1[3] * v1[3])); }
;                 }
;                 if (XB) { sq += __shfl_xor(sq, 16); sq += __shfl_xor(sq, 32); if (fq == 0) SS[(size_t)row * 32 + u.pn * 4 + wc] = sq; }
;             }
.LBB0_1218:
	v_lshlrev_b32_e32 v42, 16, v80
	v_and_b32_e32 v43, 0xffff0000, v80
	v_lshlrev_b32_e32 v44, 16, v81
	v_and_b32_e32 v45, 0xffff0000, v81
	v_lshlrev_b32_e32 v46, 16, v82
	v_and_b32_e32 v47, 0xffff0000, v82
	v_lshlrev_b32_e32 v50, 16, v83
	v_and_b32_e32 v51, 0xffff0000, v83
	v_pk_add_f32 v[38:39], v[38:39], v[44:45]
	v_pk_add_f32 v[36:37], v[36:37], v[42:43]
	v_pk_add_f32 v[34:35], v[34:35], v[50:51]
	v_pk_add_f32 v[32:33], v[32:33], v[46:47]
	v_cvt_pk_bf16_f32 v42, v36, v37
	v_cvt_pk_bf16_f32 v43, v38, v39
	v_cvt_pk_bf16_f32 v44, v32, v33
	v_cvt_pk_bf16_f32 v45, v34, v35
	s_and_b64 vcc, exec, s[6:7]
	global_store_dwordx4 v[48:49], v[42:45], off offset:256
	s_cbranch_vccnz .LBB0_1222
	v_mul_f32_e32 v33, v33, v33
	v_mul_f32_e32 v37, v37, v37
	v_fmac_f32_e32 v33, v32, v32
	v_mul_f32_e32 v32, v35, v35
	v_fmac_f32_e32 v37, v36, v36
	v_mul_f32_e32 v36, v39, v39
	v_fmac_f32_e32 v32, v34, v34
	v_and_b32_e32 v34, 64, v184
	v_fmac_f32_e32 v36, v38, v38
	v_add_f32_e32 v32, v33, v32
	v_xor_b32_e32 v33, 16, v184
	v_add_u32_e32 v34, 64, v34
	v_add_f32_e32 v36, v37, v36
	v_cmp_lt_i32_e32 vcc, v33, v34
	v_add_f32_e32 v32, v36, v32
	v_add_f32_e32 v32, v32, v40
	v_cndmask_b32_e32 v33, v184, v33, vcc
	v_lshlrev_b32_e32 v33, 2, v33
	ds_bpermute_b32 v33, v33, v32
	s_waitcnt lgkmcnt(0)
	v_add_f32_e32 v32, v32, v33
	v_xor_b32_e32 v33, 32, v184
	v_cmp_lt_i32_e32 vcc, v33, v34
	s_nop 1
	v_cndmask_b32_e32 v33, v184, v33, vcc
	v_lshlrev_b32_e32 v33, 2, v33
	ds_bpermute_b32 v33, v33, v32
	s_and_saveexec_b64 s[28:29], s[2:3]
	s_cbranch_execz .LBB0_1221
	v_lshlrev_b64 v[34:35], 7, v[96:97]
	v_lshl_add_u64 v[34:35], s[64:65], 0, v[34:35]
	v_lshl_add_u64 v[34:35], s[26:27], 2, v[34:35]
	s_lshl_b32 s8, s38, 2
	v_lshl_add_u64 v[34:35], v[34:35], 0, s[8:9]
	s_waitcnt lgkmcnt(0)
	v_add_f32_e32 v32, v32, v33
	global_store_dword v[34:35], v32, off

; __device__ __forceinline__ unsigned cvt_pk_bf16(float lo, float hi) { f32x2 v = {lo, hi}; return __builtin_bit_cast(unsigned, __builtin_convertvector(v, bf2_t)); }
;     __device__ __forceinline__ void operator()(const f32x4 (&acc)[2][2][4][2], const Unit& u, int wr, int wc, int fr, int fq) const {
;     ...
;             for (int m = 0; m < 4; ++m) {
;                 const int row = row0 + ai * HALF + m * 16;
;                 const size_t off = (size_t)row * 2048 + col0;
;                 float sq = 0.f;
; #pragma unroll
;                 for (int bj = 0; bj < 2; ++bj) {
;                     const u32x4 w = raw[m][bj];
;                     const f32x4 r0 = {__uint_as_float(w.x << 16), __uint_as_float(w.x & 0xffff0000u), __uint_as_float(w.y << 16), __uint_as_float(w.y & 0xffff0000u)};
;                     const f32x4 r1 = {__uint_as_float(w.z << 16), __uint_as_float(w.z & 0xffff0000u), __uint_as_float(w.w << 16), __uint_as_float(w.w & 0xffff0000u)};
;                     const f32x4 v0 = r0 + acc[ai][bj][m][0], v1 = r1 + acc[ai][bj][m][1];
;                     if (out32) { *(f32x4*)(out32 + off + bj * HALF) = v0; *(f32x4*)(out32 + off + bj * HALF + 4) = v1; }
;                     if (XB) { u32x4 o; o.x = cvt_pk_bf16(v0[0], v0[1]); o.y = cvt_pk_bf16(v0[2], v0[3]); o.z = cvt_pk_bf16(v1[0], v1[1]); o.w = cvt_pk_bf16(v1[2], v1[3]);
;                               *(u32x4*)(XB + off + bj * HALF) = o;
;                               sq += ((v0[0] * v0[0] + v0[1] * v0[1]) + (v0[2] * v0[2] + v0[3] * v0[3])) + ((v1[0] * v1[0] + v1[1] * v1[1]) + (v1[2] * v1[2] + v1[3] * v1[3])); }
;                 }
;                 if (XB) { sq += __shfl_xor(sq, 16); sq += __shfl_xor(sq, 32); if (fq == 0) SS[(size_t)row * 32 + u.pn * 4 + wc] = sq; }
;             }
.LBB0_1225:
	v_lshlrev_b32_e32 v26, 16, v72
	v_and_b32_e32 v27, 0xffff0000, v72
	v_lshlrev_b32_e32 v28, 16, v73
	v_and_b32_e32 v29, 0xffff0000, v73
	v_lshlrev_b32_e32 v30, 16, v74
	v_and_b32_e32 v31, 0xffff0000, v74
	v_lshlrev_b32_e32 v34, 16, v75
	v_and_b32_e32 v35, 0xffff0000, v75
	v_pk_add_f32 v[22:23], v[22:23], v[28:29]
	v_pk_add_f32 v[20:21], v[20:21], v[26:27]
	v_pk_add_f32 v[18:19], v[18:19], v[34:35]
	v_pk_add_f32 v[16:17], v[16:17], v[30:31]
	v_cvt_pk_bf16_f32 v26, v20, v21
	v_cvt_pk_bf16_f32 v27, v22, v23
	v_cvt_pk_bf16_f32 v28, v16, v17
	v_cvt_pk_bf16_f32 v29, v18, v19
	s_and_b64 vcc, exec, s[6:7]
	global_store_dwordx4 v[32:33], v[26:29], off offset:256
	s_cbranch_vccnz .LBB0_1229
	v_mul_f32_e32 v17, v17, v17
	v_mul_f32_e32 v21, v21, v21
	v_fmac_f32_e32 v17, v16, v16
	v_mul_f32_e32 v16, v19, v19
	v_fmac_f32_e32 v21, v20, v20
	v_mul_f32_e32 v20, v23, v23
	v_fmac_f32_e32 v16, v18, v18
	v_and_b32_e32 v18, 64, v184
	v_fmac_f32_e32 v20, v22, v22
	v_add_f32_e32 v16, v17, v16
	v_xor_b32_e32 v17, 16, v184
	v_add_u32_e32 v18, 64, v18
	v_add_f32_e32 v20, v21, v20
	v_cmp_lt_i32_e32 vcc, v17, v18
	v_add_f32_e32 v16, v20, v16
	v_add_f32_e32 v16, v16, v24
	v_cndmask_b32_e32 v17, v184, v17, vcc
	v_lshlrev_b32_e32 v17, 2, v17
	ds_bpermute_b32 v17, v17, v16
	s_waitcnt lgkmcnt(0)
	v_add_f32_e32 v16, v16, v17
	v_xor_b32_e32 v17, 32, v184
	v_cmp_lt_i32_e32 vcc, v17, v18
	s_nop 1
	v_cndmask_b32_e32 v17, v184, v17, vcc
	v_lshlrev_b32_e32 v17, 2, v17
	ds_bpermute_b32 v17, v17, v16
	s_and_saveexec_b64 s[28:29], s[2:3]
	s_cbranch_execz .LBB0_1228
	v_lshlrev_b64 v[18:19], 7, v[94:95]
	v_lshl_add_u64 v[18:19], s[64:65], 0, v[18:19]
	v_lshl_add_u64 v[18:19], s[26:27], 2, v[18:19]
	s_lshl_b32 s8, s38, 2
	v_lshl_add_u64 v[18:19], v[18:19], 0, s[8:9]
	s_waitcnt lgkmcnt(0)
	v_add_f32_e32 v16, v16, v17
	global_store_dword v[18:19], v16, off

; __device__ __forceinline__ unsigned cvt_pk_bf16(float lo, float hi) { f32x2 v = {lo, hi}; return __builtin_bit_cast(unsigned, __builtin_convertvector(v, bf2_t)); }
;     __device__ __forceinline__ void operator()(const f32x4 (&acc)[2][2][4][2], const Unit& u, int wr, int wc, int fr, int fq) const {
;     ...
;             for (int m = 0; m < 4; ++m) {
;                 const int row = row0 + ai * HALF + m * 16;
;                 const size_t off = (size_t)row * 2048 + col0;
;                 float sq = 0.f;
; #pragma unroll
;                 for (int bj = 0; bj < 2; ++bj) {
;                     const u32x4 w = raw[m][bj];
;                     const f32x4 r0 = {__uint_as_float(w.x << 16), __uint_as_float(w.x & 0xffff0000u), __uint_as_float(w.y << 16), __uint_as_float(w.y & 0xffff0000u)};
;                     const f32x4 r1 = {__uint_as_float(w.z << 16), __uint_as_float(w.z & 0xffff0000u), __uint_as_float(w.w << 16), __uint_as_float(w.w & 0xffff0000u)};
;                     const f32x4 v0 = r0 + acc[ai][bj][m][0], v1 = r1 + acc[ai][bj][m][1];
;                     if (out32) { *(f32x4*)(out32 + off + bj * HALF) = v0; *(f32x4*)(out32 + off + bj * HALF + 4) = v1; }
;                     if (XB) { u32x4 o; o.x = cvt_pk_bf16(v0[0], v0[1]); o.y = cvt_pk_bf16(v0[2], v0[3]); o.z = cvt_pk_bf16(v1[0], v1[1]); o.w = cvt_pk_bf16(v1[2], v1[3]);
;                               *(u32x4*)(XB + off + bj * HALF) = o;
;                               sq += ((v0[0] * v0[0] + v0[1] * v0[1]) + (v0[2] * v0[2] + v0[3] * v0[3])) + ((v1[0] * v1[0] + v1[1] * v1[1]) + (v1[2] * v1[2] + v1[3] * v1[3])); }
;                 }
;                 if (XB) { sq += __shfl_xor(sq, 16); sq += __shfl_xor(sq, 32); if (fq == 0) SS[(size_t)row * 32 + u.pn * 4 + wc] = sq; }
;             }
.LBB0_1232:
	v_lshlrev_b32_e32 v10, 16, v64
	v_and_b32_e32 v11, 0xffff0000, v64
	v_lshlrev_b32_e32 v12, 16, v65
	v_and_b32_e32 v13, 0xffff0000, v65
	v_lshlrev_b32_e32 v14, 16, v66
	v_and_b32_e32 v15, 0xffff0000, v66
	v_pk_add_f32 v[6:7], v[6:7], v[12:13]
	v_pk_add_f32 v[4:5], v[4:5], v[10:11]
	v_lshlrev_b32_e32 v18, 16, v67
	v_and_b32_e32 v19, 0xffff0000, v67
	v_pk_add_f32 v[12:13], v[0:1], v[14:15]
	v_mul_f32_e32 v0, v5, v5
	v_mul_f32_e32 v1, v7, v7
	v_pk_add_f32 v[10:11], v[2:3], v[18:19]
	v_fmac_f32_e32 v0, v4, v4
	v_fmac_f32_e32 v1, v6, v6
	v_add_f32_e32 v0, v0, v1
	v_mul_f32_e32 v1, v13, v13
	v_mul_f32_e32 v2, v11, v11
	v_fmac_f32_e32 v1, v12, v12
	v_fmac_f32_e32 v2, v10, v10
	v_add_f32_e32 v1, v1, v2
	v_and_b32_e32 v2, 64, v184
	v_add_f32_e32 v0, v0, v1
	v_xor_b32_e32 v1, 16, v184
	v_add_u32_e32 v3, 64, v2
	v_cmp_lt_i32_e32 vcc, v1, v3
	v_add_f32_e32 v0, v0, v8
	v_cvt_pk_bf16_f32 v2, v4, v5
	v_cndmask_b32_e32 v1, v184, v1, vcc
	v_lshlrev_b32_e32 v1, 2, v1
	ds_bpermute_b32 v1, v1, v0
	v_cvt_pk_bf16_f32 v4, v12, v13
	v_cvt_pk_bf16_f32 v5, v10, v11
	s_waitcnt lgkmcnt(0)
	v_add_f32_e32 v0, v0, v1
	v_xor_b32_e32 v1, 32, v184
	v_cmp_lt_i32_e32 vcc, v1, v3
	v_cvt_pk_bf16_f32 v3, v6, v7
	global_store_dwordx4 v[16:17], v[2:5], off offset:256
	v_cndmask_b32_e32 v1, v184, v1, vcc
	v_lshlrev_b32_e32 v1, 2, v1
	ds_bpermute_b32 v1, v1, v0
	s_and_saveexec_b64 s[6:7], s[2:3]
	s_cbranch_execz .LBB0_1234
	v_lshlrev_b64 v[2:3], 7, v[92:93]
	v_lshl_add_u64 v[2:3], s[64:65], 0, v[2:3]
	v_lshl_add_u64 v[2:3], s[26:27], 2, v[2:3]
	s_lshl_b32 s8, s38, 2
	v_lshl_add_u64 v[2:3], v[2:3], 0, s[8:9]
	s_waitcnt lgkmcnt(0)
	v_add_f32_e32 v0, v0, v1
	global_store_dword v[2:3], v0, off

;     __device__ bool next(int i, pg8::Unit& u) const { const int cnt = (nwg - c + G - 1) / G; if (i >= reps * cnt) return false; return pg8::StaticOrder::next(i % cnt, u); }
; template <class Epi, class Sched, bool ALIGN_EPI = false, bool SP2 = false>
; __device__ __forceinline__ void gemm_phase(PG8_LAS unsigned char* lds, const Gemm g, const Sched& S, const Epi& E) {
;     ...
;         const bool has_next = S.next(ui + 1, nxt);
;         const char* nA = has_next ? (const char*)g.A + (size_t)nxt.pm * tstep : cA; const char* nB = has_next ? (const char*)g.Bt + (size_t)nxt.pn * tstep : cB;
;         for (int t = 0; t < nt; t += 2) {
;             const bool last = (t == nt - 2);
;             const char* a1 = cA + (size_t)(t + 1) * kstep;
;             const char* a2 = last ? nA : cA + (size_t)(t + 2) * kstep; const char* b2 = last ? nB : cB + (size_t)(t + 2) * kstep;
;     ...
; #pragma unroll
;         for (int a = 0; a < 2; ++a)
; #pragma unroll
;             for (int b = 0; b < 2; ++b)
; #pragma unroll
;                 for (int m = 0; m < 4; ++m)
; #pragma unroll
;                     for (int n = 0; n < 2; ++n) acc[a][b][m][n] = (f32x4){0.f, 0.f, 0.f, 0.f};
.LBB0_1372:
	s_ashr_i32 s29, s28, 31
	s_lshl_b64 s[34:35], s[28:29], 20
	s_add_u32 s34, s74, s34
	s_addc_u32 s35, s75, s35
	s_and_b64 s[36:37], s[30:31], exec
	s_cselect_b32 s29, s35, s9
	s_cselect_b32 s39, s34, s8
	s_ashr_i32 s27, s26, 31
	s_lshl_b64 s[36:37], s[26:27], 20
	v_readlane_b32 s44, v254, 22
	v_readlane_b32 s45, v254, 23
	s_add_u32 s36, s44, s36
	s_addc_u32 s37, s45, s37
	s_and_b64 s[44:45], s[30:31], exec
	s_cselect_b32 s27, s37, s43
	s_cselect_b32 s41, s36, s42
	s_add_u32 s8, s8, 0x80080
	s_addc_u32 s9, s9, 0
	s_add_u32 s48, s42, 0x100
	v_mov_b64_e32 v[0:1], 0
	v_mov_b64_e32 v[2:3], 0
	v_mov_b64_e32 v[4:5], 0
	v_mov_b64_e32 v[6:7], 0
	v_mov_b64_e32 v[8:9], 0
	v_mov_b64_e32 v[10:11], 0
	v_mov_b64_e32 v[12:13], 0
	v_mov_b64_e32 v[14:15], 0
	v_mov_b64_e32 v[16:17], 0
	v_mov_b64_e32 v[18:19], 0
	v_mov_b64_e32 v[20:21], 0
	v_mov_b64_e32 v[22:23], 0
	v_mov_b64_e32 v[24:25], 0
	v_mov_b64_e32 v[26:27], 0
	v_mov_b64_e32 v[28:29], 0
	v_mov_b64_e32 v[30:31], 0
	v_mov_b64_e32 v[32:33], 0
	v_mov_b64_e32 v[34:35], 0
	v_mov_b64_e32 v[36:37], 0
	v_mov_b64_e32 v[38:39], 0
	v_mov_b64_e32 v[40:41], 0
	v_mov_b64_e32 v[42:43], 0
	v_mov_b64_e32 v[44:45], 0
	v_mov_b64_e32 v[46:47], 0
	v_mov_b64_e32 v[48:49], 0
	v_mov_b64_e32 v[50:51], 0
	v_mov_b64_e32 v[52:53], 0
	v_mov_b64_e32 v[54:55], 0
	v_mov_b64_e32 v[56:57], 0
	v_mov_b64_e32 v[58:59], 0
	v_mov_b64_e32 v[60:61], 0
	v_mov_b64_e32 v[62:63], 0
	v_mov_b64_e32 v[64:65], 0
	v_mov_b64_e32 v[66:67], 0
	v_mov_b64_e32 v[68:69], 0
	v_mov_b64_e32 v[70:71], 0
	v_mov_b64_e32 v[72:73], 0
	v_mov_b64_e32 v[74:75], 0
	v_mov_b64_e32 v[76:77], 0
	v_mov_b64_e32 v[78:79], 0
	v_mov_b64_e32 v[80:81], 0
	v_mov_b64_e32 v[82:83], 0
	v_mov_b64_e32 v[84:85], 0
	v_mov_b64_e32 v[86:87], 0
	v_mov_b64_e32 v[88:89], 0
	v_mov_b64_e32 v[90:91], 0
	v_mov_b64_e32 v[92:93], 0
	v_mov_b64_e32 v[94:95], 0
	v_mov_b64_e32 v[96:97], 0
	v_mov_b64_e32 v[98:99], 0
	v_mov_b64_e32 v[100:101], 0
	v_mov_b64_e32 v[102:103], 0
	v_mov_b64_e32 v[104:105], 0
	v_mov_b64_e32 v[106:107], 0
	v_mov_b64_e32 v[124:125], 0
	v_mov_b64_e32 v[126:127], 0
	v_mov_b64_e32 v[128:129], 0
	v_mov_b64_e32 v[130:131], 0
	v_mov_b64_e32 v[132:133], 0
	v_mov_b64_e32 v[134:135], 0
	v_mov_b64_e32 v[136:137], 0
	v_mov_b64_e32 v[138:139], 0
	v_mov_b64_e32 v[140:141], 0
	v_mov_b64_e32 v[142:143], 0
	s_addc_u32 s49, s43, 0
	s_mov_b32 s66, -2

;     __device__ bool next(int i, pg8::Unit& u) const { const int cnt = (nwg - c + G - 1) / G; if (i >= reps * cnt) return false; return pg8::StaticOrder::next(i % cnt, u); }
; template <class Epi, class Sched, bool ALIGN_EPI = false, bool SP2 = false>
; __device__ __forceinline__ void gemm_phase(PG8_LAS unsigned char* lds, const Gemm g, const Sched& S, const Epi& E) {
;     ...
;         const bool has_next = S.next(ui + 1, nxt);
;         const char* nA = has_next ? (const char*)g.A + (size_t)nxt.pm * tstep : cA; const char* nB = has_next ? (const char*)g.Bt + (size_t)nxt.pn * tstep : cB;
;         for (int t = 0; t < nt; t += 2) {
;             const bool last = (t == nt - 2);
;             const char* a1 = cA + (size_t)(t + 1) * kstep;
;             const char* a2 = last ? nA : cA + (size_t)(t + 2) * kstep; const char* b2 = last ? nB : cB + (size_t)(t + 2) * kstep;
;     ...
; #pragma unroll
;         for (int a = 0; a < 2; ++a)
; #pragma unroll
;             for (int b = 0; b < 2; ++b)
; #pragma unroll
;                 for (int m = 0; m < 4; ++m)
; #pragma unroll
;                     for (int n = 0; n < 2; ++n) acc[a][b][m][n] = (f32x4){0.f, 0.f, 0.f, 0.f};
.LBB0_1548:
	s_ashr_i32 s13, s12, 31
	s_lshl_b64 s[14:15], s[12:13], 20
	s_add_u32 s14, s60, s14
	s_addc_u32 s15, s61, s15
	s_and_b64 s[16:17], s[0:1], exec
	s_cselect_b32 s13, s15, s21
	s_cselect_b32 s39, s14, s20
	s_ashr_i32 s11, s10, 31
	s_lshl_b64 s[16:17], s[10:11], 20
	s_add_u32 s16, s72, s16
	s_addc_u32 s17, s73, s17
	s_and_b64 s[24:25], s[0:1], exec
	s_cselect_b32 s11, s17, s23
	s_cselect_b32 s40, s16, s22
	s_add_u32 s20, s20, 0x80080
	s_addc_u32 s21, s21, 0
	s_add_u32 s41, s22, 0x100
	v_mov_b64_e32 v[0:1], 0
	v_mov_b64_e32 v[2:3], 0
	v_mov_b64_e32 v[4:5], 0
	v_mov_b64_e32 v[6:7], 0
	v_mov_b64_e32 v[8:9], 0
	v_mov_b64_e32 v[10:11], 0
	v_mov_b64_e32 v[12:13], 0
	v_mov_b64_e32 v[14:15], 0
	v_mov_b64_e32 v[16:17], 0
	v_mov_b64_e32 v[18:19], 0
	v_mov_b64_e32 v[20:21], 0
	v_mov_b64_e32 v[22:23], 0
	v_mov_b64_e32 v[24:25], 0
	v_mov_b64_e32 v[26:27], 0
	v_mov_b64_e32 v[28:29], 0
	v_mov_b64_e32 v[30:31], 0
	v_mov_b64_e32 v[32:33], 0
	v_mov_b64_e32 v[34:35], 0
	v_mov_b64_e32 v[36:37], 0
	v_mov_b64_e32 v[38:39], 0
	v_mov_b64_e32 v[40:41], 0
	v_mov_b64_e32 v[42:43], 0
	v_mov_b64_e32 v[44:45], 0
	v_mov_b64_e32 v[46:47], 0
	v_mov_b64_e32 v[48:49], 0
	v_mov_b64_e32 v[50:51], 0
	v_mov_b64_e32 v[52:53], 0
	v_mov_b64_e32 v[54:55], 0
	v_mov_b64_e32 v[56:57], 0
	v_mov_b64_e32 v[58:59], 0
	v_mov_b64_e32 v[60:61], 0
	v_mov_b64_e32 v[62:63], 0
	v_mov_b64_e32 v[64:65], 0
	v_mov_b64_e32 v[66:67], 0
	v_mov_b64_e32 v[68:69], 0
	v_mov_b64_e32 v[70:71], 0
	v_mov_b64_e32 v[72:73], 0
	v_mov_b64_e32 v[74:75], 0
	v_mov_b64_e32 v[76:77], 0
	v_mov_b64_e32 v[78:79], 0
	v_mov_b64_e32 v[80:81], 0
	v_mov_b64_e32 v[82:83], 0
	v_mov_b64_e32 v[84:85], 0
	v_mov_b64_e32 v[86:87], 0
	v_mov_b64_e32 v[88:89], 0
	v_mov_b64_e32 v[90:91], 0
	v_mov_b64_e32 v[92:93], 0
	v_mov_b64_e32 v[94:95], 0
	v_mov_b64_e32 v[96:97], 0
	v_mov_b64_e32 v[98:99], 0
	v_mov_b64_e32 v[100:101], 0
	v_mov_b64_e32 v[102:103], 0
	v_mov_b64_e32 v[104:105], 0
	v_mov_b64_e32 v[106:107], 0
	v_mov_b64_e32 v[108:109], 0
	v_mov_b64_e32 v[110:111], 0
	v_mov_b64_e32 v[112:113], 0
	v_mov_b64_e32 v[114:115], 0
	v_mov_b64_e32 v[116:117], 0
	v_mov_b64_e32 v[118:119], 0
	v_mov_b64_e32 v[120:121], 0
	v_mov_b64_e32 v[122:123], 0
	v_mov_b64_e32 v[124:125], 0
	v_mov_b64_e32 v[126:127], 0
	s_addc_u32 s42, s23, 0
	s_mov_b32 s43, -2
